# EPI-PIPE2: split-tile finish epilogues of GEMM2/GEMM4 - residual loads five row groups ahead through a slot ring, vmcnt re-derived, stores never waited for (on SUBLN-LDS)
# speedup vs baseline: 1.0054x; 1.0054x over previous
.LBB0_1084:
	s_add_i32 s47, s3, 1
	s_cmp_gt_u32 s3, 1
	s_mov_b64 s[30:31], -1
	buffer_inv sc1
	s_cbranch_scc0 .LBB0_1086
	s_and_b32 s31, s47, 3
	s_lshl_b32 s30, s72, 2
	s_or_b32 s31, s31, s30
	s_mul_i32 s31, s31, 0x18000
	s_add_i32 s31, s31, s45
	s_add_i32 s49, s31, 0x10000
	buffer_load_dwordx4 v[138:141], v193, s[8:11], s49 offen
	s_add_i32 s49, s31, 0x10400
	buffer_load_dwordx4 v[142:145], v193, s[8:11], s49 offen
	s_add_i32 s49, s31, 0x10800
	buffer_load_dwordx4 v[146:149], v193, s[8:11], s49 offen
	s_add_i32 s49, s31, 0x10c00
	buffer_load_dwordx4 v[150:153], v193, s[8:11], s49 offen
	s_add_i32 s49, s31, 0x11000
	buffer_load_dwordx4 v[154:157], v193, s[8:11], s49 offen
	s_add_i32 s49, s31, 0x11400
	buffer_load_dwordx4 v[158:161], v193, s[8:11], s49 offen
	s_add_i32 s49, s31, 0x11800
	s_add_i32 s31, s31, 0x11c00
	buffer_load_dwordx4 v[134:137], v193, s[8:11], s49 offen
	buffer_load_dwordx4 v[130:133], v193, s[8:11], s31 offen
	s_or_b32 s31, s3, s30
	s_xor_b32 s31, s31, 2
	s_mul_i32 s31, s31, 0x18000
	s_add_i32 s31, s31, s45
	s_add_i32 s49, s31, 0x8000
	s_waitcnt vmcnt(7)
	v_cvt_f32_f16_e32 v164, v140
	v_cvt_f32_f16_sdwa v165, v140 dst_sel:DWORD dst_unused:UNUSED_PAD src0_sel:WORD_1
	v_cvt_f32_f16_e32 v140, v141
	v_cvt_f32_f16_sdwa v141, v141 dst_sel:DWORD dst_unused:UNUSED_PAD src0_sel:WORD_1
	s_waitcnt vmcnt(6)
	v_cvt_f32_f16_e32 v198, v142
	v_cvt_f32_f16_sdwa v199, v142 dst_sel:DWORD dst_unused:UNUSED_PAD src0_sel:WORD_1
	v_cvt_f32_f16_e32 v142, v143
	v_cvt_f32_f16_sdwa v143, v143 dst_sel:DWORD dst_unused:UNUSED_PAD src0_sel:WORD_1
	v_cvt_f32_f16_e32 v210, v144
	v_cvt_f32_f16_sdwa v211, v144 dst_sel:DWORD dst_unused:UNUSED_PAD src0_sel:WORD_1
	v_cvt_f32_f16_e32 v144, v145
	v_cvt_f32_f16_sdwa v145, v145 dst_sel:DWORD dst_unused:UNUSED_PAD src0_sel:WORD_1
	s_waitcnt vmcnt(5)
	v_cvt_f32_f16_e32 v212, v146
	v_cvt_f32_f16_sdwa v213, v146 dst_sel:DWORD dst_unused:UNUSED_PAD src0_sel:WORD_1
	v_cvt_f32_f16_e32 v146, v147
	v_cvt_f32_f16_sdwa v147, v147 dst_sel:DWORD dst_unused:UNUSED_PAD src0_sel:WORD_1
	v_cvt_f32_f16_e32 v214, v148
	v_cvt_f32_f16_sdwa v215, v148 dst_sel:DWORD dst_unused:UNUSED_PAD src0_sel:WORD_1
	v_cvt_f32_f16_e32 v148, v149
	v_cvt_f32_f16_sdwa v149, v149 dst_sel:DWORD dst_unused:UNUSED_PAD src0_sel:WORD_1
	s_waitcnt vmcnt(4)
	v_cvt_f32_f16_e32 v216, v150
	v_cvt_f32_f16_sdwa v217, v150 dst_sel:DWORD dst_unused:UNUSED_PAD src0_sel:WORD_1
	v_cvt_f32_f16_e32 v150, v151
	v_cvt_f32_f16_sdwa v151, v151 dst_sel:DWORD dst_unused:UNUSED_PAD src0_sel:WORD_1
	v_cvt_f32_f16_e32 v218, v152
	v_cvt_f32_f16_sdwa v219, v152 dst_sel:DWORD dst_unused:UNUSED_PAD src0_sel:WORD_1
	v_cvt_f32_f16_e32 v152, v153
	v_cvt_f32_f16_sdwa v153, v153 dst_sel:DWORD dst_unused:UNUSED_PAD src0_sel:WORD_1
	s_waitcnt vmcnt(3)
	v_cvt_f32_f16_e32 v220, v154
	v_cvt_f32_f16_sdwa v221, v154 dst_sel:DWORD dst_unused:UNUSED_PAD src0_sel:WORD_1
	v_cvt_f32_f16_e32 v154, v155
	v_cvt_f32_f16_sdwa v155, v155 dst_sel:DWORD dst_unused:UNUSED_PAD src0_sel:WORD_1
	v_cvt_f32_f16_e32 v222, v156
	v_cvt_f32_f16_sdwa v223, v156 dst_sel:DWORD dst_unused:UNUSED_PAD src0_sel:WORD_1
	v_cvt_f32_f16_e32 v156, v157
	v_cvt_f32_f16_sdwa v157, v157 dst_sel:DWORD dst_unused:UNUSED_PAD src0_sel:WORD_1
	v_cvt_f32_f16_e32 v162, v138
	v_cvt_f32_f16_sdwa v163, v138 dst_sel:DWORD dst_unused:UNUSED_PAD src0_sel:WORD_1
	v_cvt_f32_f16_e32 v138, v139
	v_cvt_f32_f16_sdwa v139, v139 dst_sel:DWORD dst_unused:UNUSED_PAD src0_sel:WORD_1
	v_pk_add_f32 v[124:125], v[124:125], v[140:141]
	v_pk_add_f32 v[120:121], v[120:121], v[142:143]
	v_pk_add_f32 v[140:141], v[116:117], v[144:145]
	v_pk_add_f32 v[144:145], v[112:113], v[146:147]
	v_pk_add_f32 v[142:143], v[110:111], v[212:213]
	v_pk_add_f32 v[148:149], v[108:109], v[148:149]
	v_pk_add_f32 v[146:147], v[106:107], v[214:215]
	v_pk_add_f32 v[112:113], v[104:105], v[150:151]
	v_pk_add_f32 v[110:111], v[102:103], v[216:217]
	v_pk_add_f32 v[108:109], v[100:101], v[152:153]
	v_pk_add_f32 v[106:107], v[98:99], v[218:219]
	v_pk_add_f32 v[100:101], v[96:97], v[154:155]
	v_pk_add_f32 v[98:99], v[94:95], v[220:221]
	v_pk_add_f32 v[104:105], v[92:93], v[156:157]
	v_pk_add_f32 v[102:103], v[90:91], v[222:223]
	s_waitcnt vmcnt(1)
	v_cvt_f32_f16_e32 v90, v134
	v_cvt_f32_f16_sdwa v91, v134 dst_sel:DWORD dst_unused:UNUSED_PAD src0_sel:WORD_1
	v_cvt_f32_f16_e32 v92, v135
	v_cvt_f32_f16_sdwa v93, v135 dst_sel:DWORD dst_unused:UNUSED_PAD src0_sel:WORD_1
	v_cvt_f32_f16_e32 v94, v136
	v_cvt_f32_f16_e32 v96, v137
	v_cvt_f32_f16_sdwa v97, v137 dst_sel:DWORD dst_unused:UNUSED_PAD src0_sel:WORD_1
	v_cvt_f32_f16_sdwa v95, v136 dst_sel:DWORD dst_unused:UNUSED_PAD src0_sel:WORD_1
	v_pk_add_f32 v[128:129], v[128:129], v[138:139]
	v_pk_add_f32 v[126:127], v[126:127], v[162:163]
	v_pk_add_f32 v[122:123], v[122:123], v[164:165]
	v_cvt_f32_f16_e32 v224, v158
	v_cvt_f32_f16_sdwa v225, v158 dst_sel:DWORD dst_unused:UNUSED_PAD src0_sel:WORD_1
	v_cvt_f32_f16_e32 v158, v159
	v_cvt_f32_f16_sdwa v159, v159 dst_sel:DWORD dst_unused:UNUSED_PAD src0_sel:WORD_1
	v_cvt_f32_f16_e32 v226, v160
	v_cvt_f32_f16_sdwa v227, v160 dst_sel:DWORD dst_unused:UNUSED_PAD src0_sel:WORD_1
	v_cvt_f32_f16_e32 v160, v161
	v_cvt_f32_f16_sdwa v161, v161 dst_sel:DWORD dst_unused:UNUSED_PAD src0_sel:WORD_1
	v_pk_add_f32 v[118:119], v[118:119], v[198:199]
	v_pk_add_f32 v[138:139], v[114:115], v[210:211]
	v_pk_add_f32 v[80:81], v[80:81], v[92:93]
	v_pk_add_f32 v[78:79], v[78:79], v[90:91]
	v_pk_add_f32 v[76:77], v[76:77], v[96:97]
	v_pk_add_f32 v[74:75], v[74:75], v[94:95]
	s_waitcnt vmcnt(0)
	v_cvt_f32_f16_e32 v90, v130
	v_cvt_f32_f16_sdwa v91, v130 dst_sel:DWORD dst_unused:UNUSED_PAD src0_sel:WORD_1
	v_cvt_f32_f16_e32 v92, v131
	v_cvt_f32_f16_sdwa v93, v131 dst_sel:DWORD dst_unused:UNUSED_PAD src0_sel:WORD_1
	v_cvt_f32_f16_e32 v94, v132
	v_cvt_f32_f16_e32 v96, v133
	v_cvt_f32_f16_sdwa v97, v133 dst_sel:DWORD dst_unused:UNUSED_PAD src0_sel:WORD_1
	v_cvt_f32_f16_sdwa v95, v132 dst_sel:DWORD dst_unused:UNUSED_PAD src0_sel:WORD_1
	v_pk_add_f32 v[88:89], v[88:89], v[158:159]
	v_pk_add_f32 v[86:87], v[86:87], v[224:225]
	v_pk_add_f32 v[84:85], v[84:85], v[160:161]
	v_pk_add_f32 v[82:83], v[82:83], v[226:227]
	v_pk_add_f32 v[72:73], v[72:73], v[92:93]
	v_pk_add_f32 v[70:71], v[70:71], v[90:91]
	v_pk_add_f32 v[68:69], v[68:69], v[96:97]
	v_pk_add_f32 v[66:67], v[66:67], v[94:95]
	s_nop 0
	buffer_load_dwordx4 v[90:93], v193, s[8:11], s49 offen
	s_add_i32 s49, s31, 0x8400
	buffer_load_dwordx4 v[94:97], v193, s[8:11], s49 offen
	s_add_i32 s49, s31, 0x8800
	buffer_load_dwordx4 v[134:137], v193, s[8:11], s49 offen
	s_add_i32 s49, s31, 0x8c00
	buffer_load_dwordx4 v[154:157], v193, s[8:11], s49 offen
	s_add_i32 s49, s31, 0x9000
	buffer_load_dwordx4 v[210:213], v193, s[8:11], s49 offen
	s_add_i32 s49, s31, 0x9400
	buffer_load_dwordx4 v[214:217], v193, s[8:11], s49 offen
	s_add_i32 s49, s31, 0x9800
	s_add_i32 s31, s31, 0x9c00
	buffer_load_dwordx4 v[130:133], v193, s[8:11], s49 offen
	buffer_load_dwordx4 v[114:117], v193, s[8:11], s31 offen
	s_add_i32 s31, s3, -1
	s_and_b32 s31, s31, 3
	s_or_b32 s30, s31, s30
	s_mul_i32 s30, s30, 0x18000
	s_add_i32 s30, s45, s30
	s_or_b32 s31, s30, 0x400
	s_waitcnt vmcnt(7)
	v_cvt_f32_f16_e32 v150, v90
	v_cvt_f32_f16_sdwa v151, v90 dst_sel:DWORD dst_unused:UNUSED_PAD src0_sel:WORD_1
	v_cvt_f32_f16_e32 v90, v91
	v_cvt_f32_f16_sdwa v91, v91 dst_sel:DWORD dst_unused:UNUSED_PAD src0_sel:WORD_1
	v_cvt_f32_f16_e32 v152, v92
	v_cvt_f32_f16_sdwa v153, v92 dst_sel:DWORD dst_unused:UNUSED_PAD src0_sel:WORD_1
	s_waitcnt vmcnt(6)
	v_cvt_f32_f16_e32 v198, v94
	v_cvt_f32_f16_sdwa v199, v94 dst_sel:DWORD dst_unused:UNUSED_PAD src0_sel:WORD_1
	v_cvt_f32_f16_e32 v94, v95
	v_cvt_f32_f16_sdwa v95, v95 dst_sel:DWORD dst_unused:UNUSED_PAD src0_sel:WORD_1
	v_cvt_f32_f16_e32 v218, v96
	v_cvt_f32_f16_sdwa v219, v96 dst_sel:DWORD dst_unused:UNUSED_PAD src0_sel:WORD_1
	v_cvt_f32_f16_e32 v96, v97
	v_cvt_f32_f16_sdwa v97, v97 dst_sel:DWORD dst_unused:UNUSED_PAD src0_sel:WORD_1
	v_cvt_f32_f16_e32 v92, v93
	v_cvt_f32_f16_sdwa v93, v93 dst_sel:DWORD dst_unused:UNUSED_PAD src0_sel:WORD_1
	s_waitcnt vmcnt(4)
	v_cvt_f32_f16_e32 v224, v154
	v_cvt_f32_f16_sdwa v225, v154 dst_sel:DWORD dst_unused:UNUSED_PAD src0_sel:WORD_1
	v_pk_add_f32 v[164:165], v[128:129], v[90:91]
	v_pk_add_f32 v[158:159], v[122:123], v[152:153]
	v_pk_add_f32 v[152:153], v[120:121], v[94:95]
	v_pk_add_f32 v[120:121], v[140:141], v[96:97]
	v_cvt_f32_f16_e32 v90, v155
	v_cvt_f32_f16_sdwa v91, v155 dst_sel:DWORD dst_unused:UNUSED_PAD src0_sel:WORD_1
	v_cvt_f32_f16_e32 v94, v156
	v_cvt_f32_f16_e32 v96, v157
	v_cvt_f32_f16_sdwa v97, v157 dst_sel:DWORD dst_unused:UNUSED_PAD src0_sel:WORD_1
	v_cvt_f32_f16_sdwa v95, v156 dst_sel:DWORD dst_unused:UNUSED_PAD src0_sel:WORD_1
	v_pk_add_f32 v[160:161], v[124:125], v[92:93]
	v_pk_add_f32 v[92:93], v[112:113], v[90:91]
	v_pk_add_f32 v[90:91], v[110:111], v[224:225]
	v_pk_add_f32 v[96:97], v[108:109], v[96:97]
	v_pk_add_f32 v[94:95], v[106:107], v[94:95]
	s_waitcnt vmcnt(3)
	v_cvt_f32_f16_e32 v106, v210
	v_cvt_f32_f16_sdwa v107, v210 dst_sel:DWORD dst_unused:UNUSED_PAD src0_sel:WORD_1
	v_cvt_f32_f16_e32 v108, v211
	v_cvt_f32_f16_sdwa v109, v211 dst_sel:DWORD dst_unused:UNUSED_PAD src0_sel:WORD_1
	v_cvt_f32_f16_e32 v110, v212
	v_cvt_f32_f16_e32 v112, v213
	v_cvt_f32_f16_sdwa v113, v213 dst_sel:DWORD dst_unused:UNUSED_PAD src0_sel:WORD_1
	v_cvt_f32_f16_sdwa v111, v212 dst_sel:DWORD dst_unused:UNUSED_PAD src0_sel:WORD_1
	v_pk_add_f32 v[100:101], v[100:101], v[108:109]
	v_pk_add_f32 v[98:99], v[98:99], v[106:107]
	v_pk_add_f32 v[104:105], v[104:105], v[112:113]
	v_pk_add_f32 v[102:103], v[102:103], v[110:111]
	s_waitcnt vmcnt(2)
	v_cvt_f32_f16_e32 v106, v214
	v_cvt_f32_f16_sdwa v107, v214 dst_sel:DWORD dst_unused:UNUSED_PAD src0_sel:WORD_1
	v_cvt_f32_f16_e32 v108, v215
	v_cvt_f32_f16_sdwa v109, v215 dst_sel:DWORD dst_unused:UNUSED_PAD src0_sel:WORD_1
	v_cvt_f32_f16_e32 v110, v216
	v_cvt_f32_f16_e32 v112, v217
	v_cvt_f32_f16_sdwa v113, v217 dst_sel:DWORD dst_unused:UNUSED_PAD src0_sel:WORD_1
	v_cvt_f32_f16_sdwa v111, v216 dst_sel:DWORD dst_unused:UNUSED_PAD src0_sel:WORD_1
	v_cvt_f32_f16_e32 v220, v134
	v_cvt_f32_f16_sdwa v221, v134 dst_sel:DWORD dst_unused:UNUSED_PAD src0_sel:WORD_1
	v_cvt_f32_f16_e32 v134, v135
	v_cvt_f32_f16_sdwa v135, v135 dst_sel:DWORD dst_unused:UNUSED_PAD src0_sel:WORD_1
	v_cvt_f32_f16_e32 v222, v136
	v_cvt_f32_f16_sdwa v223, v136 dst_sel:DWORD dst_unused:UNUSED_PAD src0_sel:WORD_1
	v_cvt_f32_f16_e32 v136, v137
	v_cvt_f32_f16_sdwa v137, v137 dst_sel:DWORD dst_unused:UNUSED_PAD src0_sel:WORD_1
	v_pk_add_f32 v[108:109], v[88:89], v[108:109]
	v_pk_add_f32 v[106:107], v[86:87], v[106:107]
	v_pk_add_f32 v[112:113], v[84:85], v[112:113]
	v_pk_add_f32 v[110:111], v[82:83], v[110:111]
	s_waitcnt vmcnt(1)
	v_cvt_f32_f16_e32 v82, v130
	v_cvt_f32_f16_sdwa v83, v130 dst_sel:DWORD dst_unused:UNUSED_PAD src0_sel:WORD_1
	v_cvt_f32_f16_e32 v84, v131
	v_cvt_f32_f16_sdwa v85, v131 dst_sel:DWORD dst_unused:UNUSED_PAD src0_sel:WORD_1
	v_cvt_f32_f16_e32 v86, v132
	v_cvt_f32_f16_e32 v88, v133
	v_cvt_f32_f16_sdwa v89, v133 dst_sel:DWORD dst_unused:UNUSED_PAD src0_sel:WORD_1
	v_cvt_f32_f16_sdwa v87, v132 dst_sel:DWORD dst_unused:UNUSED_PAD src0_sel:WORD_1
	v_pk_add_f32 v[162:163], v[126:127], v[150:151]
	v_pk_add_f32 v[150:151], v[118:119], v[198:199]
	v_pk_add_f32 v[118:119], v[138:139], v[218:219]
	v_pk_add_f32 v[128:129], v[144:145], v[134:135]
	v_pk_add_f32 v[126:127], v[142:143], v[220:221]
	v_pk_add_f32 v[124:125], v[148:149], v[136:137]
	v_pk_add_f32 v[122:123], v[146:147], v[222:223]
	v_pk_add_f32 v[80:81], v[80:81], v[84:85]
	v_pk_add_f32 v[78:79], v[78:79], v[82:83]
	v_pk_add_f32 v[76:77], v[76:77], v[88:89]
	v_pk_add_f32 v[74:75], v[74:75], v[86:87]
	s_waitcnt vmcnt(0)
	v_cvt_f32_f16_e32 v82, v114
	v_cvt_f32_f16_sdwa v83, v114 dst_sel:DWORD dst_unused:UNUSED_PAD src0_sel:WORD_1
	v_cvt_f32_f16_e32 v84, v115
	v_cvt_f32_f16_sdwa v85, v115 dst_sel:DWORD dst_unused:UNUSED_PAD src0_sel:WORD_1
	v_cvt_f32_f16_e32 v86, v116
	v_cvt_f32_f16_e32 v88, v117
	v_cvt_f32_f16_sdwa v89, v117 dst_sel:DWORD dst_unused:UNUSED_PAD src0_sel:WORD_1
	v_cvt_f32_f16_sdwa v87, v116 dst_sel:DWORD dst_unused:UNUSED_PAD src0_sel:WORD_1
	v_pk_add_f32 v[136:137], v[72:73], v[84:85]
	v_pk_add_f32 v[134:135], v[70:71], v[82:83]
	v_pk_add_f32 v[140:141], v[68:69], v[88:89]
	v_pk_add_f32 v[138:139], v[66:67], v[86:87]
	s_nop 0
	buffer_load_dwordx4 v[66:69], v193, s[8:11], s30 offen
	buffer_load_dwordx4 v[70:73], v193, s[8:11], s31 offen
	s_or_b32 s31, s30, 0x800
	buffer_load_dwordx4 v[82:85], v193, s[8:11], s31 offen
	s_or_b32 s31, s30, 0xc00
	buffer_load_dwordx4 v[210:213], v193, s[8:11], s31 offen
	s_or_b32 s31, s30, 0x1000
	buffer_load_dwordx4 v[214:217], v193, s[8:11], s31 offen
	s_or_b32 s31, s30, 0x1400
	buffer_load_dwordx4 v[218:221], v193, s[8:11], s31 offen
	s_or_b32 s31, s30, 0x1800
	s_or_b32 s30, s30, 0x1c00
	buffer_load_dwordx4 v[154:157], v193, s[8:11], s31 offen
	buffer_load_dwordx4 v[146:149], v193, s[8:11], s30 offen
	s_mov_b64 s[30:31], 0
	s_waitcnt vmcnt(7)
	v_cvt_f32_f16_e32 v86, v66
	v_cvt_f32_f16_sdwa v87, v66 dst_sel:DWORD dst_unused:UNUSED_PAD src0_sel:WORD_1
	v_cvt_f32_f16_e32 v66, v67
	v_cvt_f32_f16_sdwa v67, v67 dst_sel:DWORD dst_unused:UNUSED_PAD src0_sel:WORD_1
	v_cvt_f32_f16_e32 v88, v68
	v_cvt_f32_f16_e32 v114, v69
	v_cvt_f32_f16_sdwa v115, v69 dst_sel:DWORD dst_unused:UNUSED_PAD src0_sel:WORD_1
	v_cvt_f32_f16_sdwa v89, v68 dst_sel:DWORD dst_unused:UNUSED_PAD src0_sel:WORD_1
	s_waitcnt vmcnt(6)
	v_cvt_f32_f16_e32 v68, v71
	v_cvt_f32_f16_sdwa v69, v71 dst_sel:DWORD dst_unused:UNUSED_PAD src0_sel:WORD_1
	v_pk_add_f32 v[144:145], v[164:165], v[66:67]
	v_cvt_f32_f16_e32 v66, v70
	v_cvt_f32_f16_sdwa v67, v70 dst_sel:DWORD dst_unused:UNUSED_PAD src0_sel:WORD_1
	v_cvt_f32_f16_e32 v70, v72
	v_cvt_f32_f16_sdwa v71, v72 dst_sel:DWORD dst_unused:UNUSED_PAD src0_sel:WORD_1
	v_pk_add_f32 v[116:117], v[152:153], v[68:69]
	s_waitcnt vmcnt(5)
	v_cvt_f32_f16_e32 v68, v83
	v_cvt_f32_f16_sdwa v69, v83 dst_sel:DWORD dst_unused:UNUSED_PAD src0_sel:WORD_1
	v_pk_add_f32 v[142:143], v[162:163], v[86:87]
	v_pk_add_f32 v[132:133], v[160:161], v[114:115]
	v_cvt_f32_f16_e32 v86, v73
	v_cvt_f32_f16_sdwa v87, v73 dst_sel:DWORD dst_unused:UNUSED_PAD src0_sel:WORD_1
	v_pk_add_f32 v[114:115], v[150:151], v[66:67]
	v_pk_add_f32 v[118:119], v[118:119], v[70:71]
	v_cvt_f32_f16_e32 v66, v82
	v_cvt_f32_f16_sdwa v67, v82 dst_sel:DWORD dst_unused:UNUSED_PAD src0_sel:WORD_1
	v_cvt_f32_f16_e32 v70, v84
	v_cvt_f32_f16_e32 v72, v85
	v_cvt_f32_f16_sdwa v73, v85 dst_sel:DWORD dst_unused:UNUSED_PAD src0_sel:WORD_1
	v_cvt_f32_f16_sdwa v71, v84 dst_sel:DWORD dst_unused:UNUSED_PAD src0_sel:WORD_1
	v_pk_add_f32 v[84:85], v[128:129], v[68:69]
	s_waitcnt vmcnt(4)
	v_cvt_f32_f16_e32 v68, v211
	v_cvt_f32_f16_sdwa v69, v211 dst_sel:DWORD dst_unused:UNUSED_PAD src0_sel:WORD_1
	v_pk_add_f32 v[130:131], v[158:159], v[88:89]
	v_pk_add_f32 v[120:121], v[120:121], v[86:87]
	v_pk_add_f32 v[82:83], v[126:127], v[66:67]
	v_pk_add_f32 v[88:89], v[124:125], v[72:73]
	v_pk_add_f32 v[86:87], v[122:123], v[70:71]
	v_cvt_f32_f16_e32 v66, v210
	v_cvt_f32_f16_sdwa v67, v210 dst_sel:DWORD dst_unused:UNUSED_PAD src0_sel:WORD_1
	v_cvt_f32_f16_e32 v70, v212
	v_cvt_f32_f16_e32 v72, v213
	v_cvt_f32_f16_sdwa v73, v213 dst_sel:DWORD dst_unused:UNUSED_PAD src0_sel:WORD_1
	v_cvt_f32_f16_sdwa v71, v212 dst_sel:DWORD dst_unused:UNUSED_PAD src0_sel:WORD_1
	v_pk_add_f32 v[68:69], v[92:93], v[68:69]
	s_waitcnt vmcnt(3)
	v_cvt_f32_f16_e32 v92, v215
	v_cvt_f32_f16_sdwa v93, v215 dst_sel:DWORD dst_unused:UNUSED_PAD src0_sel:WORD_1
	v_pk_add_f32 v[66:67], v[90:91], v[66:67]
	v_pk_add_f32 v[72:73], v[96:97], v[72:73]
	v_pk_add_f32 v[70:71], v[94:95], v[70:71]
	v_cvt_f32_f16_e32 v90, v214
	v_cvt_f32_f16_sdwa v91, v214 dst_sel:DWORD dst_unused:UNUSED_PAD src0_sel:WORD_1
	v_cvt_f32_f16_e32 v94, v216
	v_cvt_f32_f16_e32 v96, v217
	v_cvt_f32_f16_sdwa v97, v217 dst_sel:DWORD dst_unused:UNUSED_PAD src0_sel:WORD_1
	v_cvt_f32_f16_sdwa v95, v216 dst_sel:DWORD dst_unused:UNUSED_PAD src0_sel:WORD_1
	v_pk_add_f32 v[152:153], v[100:101], v[92:93]
	s_waitcnt vmcnt(2)
	v_cvt_f32_f16_e32 v92, v219
	v_cvt_f32_f16_sdwa v93, v219 dst_sel:DWORD dst_unused:UNUSED_PAD src0_sel:WORD_1
	v_pk_add_f32 v[150:151], v[98:99], v[90:91]
	v_pk_add_f32 v[160:161], v[104:105], v[96:97]
	v_pk_add_f32 v[158:159], v[102:103], v[94:95]
	v_cvt_f32_f16_e32 v90, v218
	v_cvt_f32_f16_sdwa v91, v218 dst_sel:DWORD dst_unused:UNUSED_PAD src0_sel:WORD_1
	v_cvt_f32_f16_e32 v94, v220
	v_cvt_f32_f16_e32 v96, v221
	v_cvt_f32_f16_sdwa v97, v221 dst_sel:DWORD dst_unused:UNUSED_PAD src0_sel:WORD_1
	v_cvt_f32_f16_sdwa v95, v220 dst_sel:DWORD dst_unused:UNUSED_PAD src0_sel:WORD_1
	v_pk_add_f32 v[124:125], v[108:109], v[92:93]
	s_waitcnt vmcnt(1)
	v_cvt_f32_f16_e32 v92, v155
	v_cvt_f32_f16_sdwa v93, v155 dst_sel:DWORD dst_unused:UNUSED_PAD src0_sel:WORD_1
	v_pk_add_f32 v[122:123], v[106:107], v[90:91]
	v_pk_add_f32 v[128:129], v[112:113], v[96:97]
	v_pk_add_f32 v[126:127], v[110:111], v[94:95]
	v_cvt_f32_f16_e32 v90, v154
	v_cvt_f32_f16_sdwa v91, v154 dst_sel:DWORD dst_unused:UNUSED_PAD src0_sel:WORD_1
	v_cvt_f32_f16_e32 v94, v156
	v_cvt_f32_f16_e32 v96, v157
	v_cvt_f32_f16_sdwa v97, v157 dst_sel:DWORD dst_unused:UNUSED_PAD src0_sel:WORD_1
	v_cvt_f32_f16_sdwa v95, v156 dst_sel:DWORD dst_unused:UNUSED_PAD src0_sel:WORD_1
	v_pk_add_f32 v[104:105], v[80:81], v[92:93]
	s_waitcnt vmcnt(0)
	v_cvt_f32_f16_e32 v80, v149
	v_cvt_f32_f16_sdwa v81, v149 dst_sel:DWORD dst_unused:UNUSED_PAD src0_sel:WORD_1
	v_pk_add_f32 v[102:103], v[78:79], v[90:91]
	v_pk_add_f32 v[112:113], v[76:77], v[96:97]
	v_pk_add_f32 v[110:111], v[74:75], v[94:95]
	v_cvt_f32_f16_e32 v74, v146
	v_cvt_f32_f16_sdwa v75, v146 dst_sel:DWORD dst_unused:UNUSED_PAD src0_sel:WORD_1
	v_cvt_f32_f16_e32 v76, v147
	v_cvt_f32_f16_sdwa v77, v147 dst_sel:DWORD dst_unused:UNUSED_PAD src0_sel:WORD_1
	v_cvt_f32_f16_e32 v78, v148
	v_cvt_f32_f16_sdwa v79, v148 dst_sel:DWORD dst_unused:UNUSED_PAD src0_sel:WORD_1
	v_pk_add_f32 v[80:81], v[140:141], v[80:81]
	v_add_u32_e32 v140, 0x80, v192
	v_ashrrev_i32_e32 v141, 31, v140
	v_pk_add_f32 v[76:77], v[136:137], v[76:77]
	v_pk_add_f32 v[74:75], v[134:135], v[74:75]
	v_pk_add_f32 v[78:79], v[138:139], v[78:79]
	v_lshl_add_u64 v[134:135], v[196:197], 2, s[12:13]
	v_lshlrev_b64 v[90:91], 12, v[140:141]
	v_lshl_add_u64 v[148:149], v[134:135], 0, v[90:91]
	global_load_dwordx4 v[106:109], v[194:195], off
	global_load_dwordx4 v[98:101], v[194:195], off offset:64
	global_load_dwordx4 v[94:97], v[194:195], off offset:512
	global_load_dwordx4 v[90:93], v[194:195], off offset:576
	s_mov_b64 s[78:79], 0x10000
	v_mov_b32_e32 v250, v148
	v_mov_b32_e32 v251, v149
	global_load_dwordx4 v[210:213], v[250:251], off
	global_load_dwordx4 v[214:217], v[250:251], off offset:64
	global_load_dwordx4 v[218:221], v[250:251], off offset:512
	global_load_dwordx4 v[222:225], v[250:251], off offset:576
	v_lshl_add_u64 v[250:251], v[250:251], 0, s[78:79]
	global_load_dwordx4 v[226:229], v[250:251], off
	global_load_dwordx4 v[230:233], v[250:251], off offset:64
	global_load_dwordx4 v[234:237], v[250:251], off offset:512
	global_load_dwordx4 v[238:241], v[250:251], off offset:576
	v_lshl_add_u64 v[250:251], v[250:251], 0, s[78:79]
	global_load_dwordx4 v[242:245], v[250:251], off
	global_load_dwordx4 v[246:249], v[250:251], off offset:64
	v_and_b32_e32 v146, 1, v1
	v_add_u32_e32 v147, 12, v209
	v_cmp_eq_u32_e32 vcc, 0, v146
	s_waitcnt vmcnt(9)
	s_nop 1
	v_mov_b32_e32 v136, v210
	v_mov_b32_e32 v137, v211
	v_mov_b32_e32 v138, v212
	v_mov_b32_e32 v139, v213
	s_nop 1
	v_pk_fma_f32 v[136:137], v[142:143], v[106:107], v[136:137]
	v_pk_fma_f32 v[144:145], v[144:145], v[108:109], v[138:139]
	s_waitcnt vmcnt(8)
	s_nop 1
	v_mov_b32_e32 v154, v214
	v_mov_b32_e32 v155, v215
	v_mov_b32_e32 v156, v216
	v_mov_b32_e32 v157, v217
	global_load_dwordx4 v[210:213], v[250:251], off offset:512
	global_load_dwordx4 v[214:217], v[250:251], off offset:576
	s_nop 1
	v_pk_fma_f32 v[130:131], v[130:131], v[98:99], v[154:155]
	v_cvt_pk_bf16_f32 v136, v136, v137
	v_cvt_pk_bf16_f32 v138, v130, v131
	v_pk_fma_f32 v[132:133], v[132:133], v[100:101], v[156:157]
	v_cvt_pk_bf16_f32 v137, v144, v145
	v_cndmask_b32_e32 v146, v147, v209, vcc
	v_add_u32_e32 v146, v146, v208
	v_ashrrev_i32_e32 v147, 31, v146
	v_cvt_pk_bf16_f32 v139, v132, v133
	v_lshlrev_b64 v[130:131], 11, v[140:141]
	v_lshl_add_u64 v[132:133], v[176:177], 0, v[130:131]
	v_lshlrev_b64 v[130:131], 1, v[146:147]
	v_permlane16_swap_b32_e32 v136, v138
	v_permlane16_swap_b32_e32 v137, v139
	v_lshl_add_u64 v[132:133], v[132:133], 0, v[130:131]
	global_store_dwordx4 v[132:133], v[136:139], off
	s_nop 0
	s_waitcnt vmcnt(10)
	s_nop 1
	v_mov_b32_e32 v136, v218
	v_mov_b32_e32 v137, v219
	v_mov_b32_e32 v138, v220
	v_mov_b32_e32 v139, v221
	s_nop 1
	v_pk_fma_f32 v[138:139], v[152:153], v[96:97], v[138:139]
	v_pk_fma_f32 v[136:137], v[150:151], v[94:95], v[136:137]
	s_waitcnt vmcnt(9)
	s_nop 1
	v_mov_b32_e32 v140, v222
	v_mov_b32_e32 v141, v223
	v_mov_b32_e32 v142, v224
	v_mov_b32_e32 v143, v225
	v_lshl_add_u64 v[250:251], v[250:251], 0, s[78:79]
	global_load_dwordx4 v[218:221], v[250:251], off
	global_load_dwordx4 v[222:225], v[250:251], off offset:64
	s_nop 1
	v_pk_fma_f32 v[142:143], v[160:161], v[92:93], v[142:143]
	v_pk_fma_f32 v[140:141], v[158:159], v[90:91], v[140:141]
	v_cvt_pk_bf16_f32 v136, v136, v137
	v_cvt_pk_bf16_f32 v137, v138, v139
	v_cvt_pk_bf16_f32 v138, v140, v141
	v_cvt_pk_bf16_f32 v139, v142, v143
	s_nop 0
	v_permlane16_swap_b32_e32 v136, v138
	v_permlane16_swap_b32_e32 v137, v139
	global_store_dwordx4 v[132:133], v[136:139], off offset:256
	v_add_u32_e32 v132, 0x90, v192
	v_ashrrev_i32_e32 v133, 31, v132
	v_lshlrev_b64 v[136:137], 12, v[132:133]
	v_lshl_add_u64 v[144:145], v[134:135], 0, v[136:137]
	v_lshlrev_b64 v[132:133], 11, v[132:133]
	v_lshl_add_u64 v[132:133], v[176:177], 0, v[132:133]
	v_lshl_add_u64 v[132:133], v[132:133], 0, v[130:131]
	s_waitcnt vmcnt(11)
	s_nop 1
	v_mov_b32_e32 v136, v226
	v_mov_b32_e32 v137, v227
	v_mov_b32_e32 v138, v228
	v_mov_b32_e32 v139, v229
	s_nop 1
	v_pk_fma_f32 v[116:117], v[116:117], v[108:109], v[138:139]
	v_pk_fma_f32 v[114:115], v[114:115], v[106:107], v[136:137]
	s_waitcnt vmcnt(10)
	s_nop 1
	v_mov_b32_e32 v140, v230
	v_mov_b32_e32 v141, v231
	v_mov_b32_e32 v142, v232
	v_mov_b32_e32 v143, v233
	global_load_dwordx4 v[226:229], v[250:251], off offset:512
	global_load_dwordx4 v[230:233], v[250:251], off offset:576
	s_nop 1
	v_pk_fma_f32 v[120:121], v[120:121], v[100:101], v[142:143]
	v_pk_fma_f32 v[118:119], v[118:119], v[98:99], v[140:141]
	v_bfe_u32 v140, v116, 16, 1
	v_bfe_u32 v141, v117, 16, 1
	v_add3_u32 v116, v116, v140, s66
	v_add3_u32 v117, v117, v141, s66
	v_lshrrev_b32_e32 v136, 16, v116
	v_cvt_pk_bf16_f32 v114, v114, v115
	v_cvt_pk_bf16_f32 v116, v118, v119
	v_and_or_b32 v115, v117, s67, v136
	v_cvt_pk_bf16_f32 v117, v120, v121
	v_permlane16_swap_b32_e32 v114, v116
	s_nop 0
	v_permlane16_swap_b32_e32 v115, v117
	global_store_dwordx4 v[132:133], v[114:117], off
	s_nop 0
	v_add_u32_e32 v136, 0xa0, v192
	v_ashrrev_i32_e32 v137, 31, v136
	v_lshlrev_b64 v[138:139], 12, v[136:137]
	v_lshl_add_u64 v[138:139], v[134:135], 0, v[138:139]
	s_waitcnt vmcnt(12)
	s_nop 1
	v_mov_b32_e32 v114, v234
	v_mov_b32_e32 v115, v235
	v_mov_b32_e32 v116, v236
	v_mov_b32_e32 v117, v237
	s_nop 1
	v_pk_fma_f32 v[116:117], v[124:125], v[96:97], v[116:117]
	v_pk_fma_f32 v[114:115], v[122:123], v[94:95], v[114:115]
	s_waitcnt vmcnt(11)
	s_nop 1
	v_mov_b32_e32 v118, v238
	v_mov_b32_e32 v119, v239
	v_mov_b32_e32 v120, v240
	v_mov_b32_e32 v121, v241
	s_nop 1
	v_pk_fma_f32 v[120:121], v[128:129], v[92:93], v[120:121]
	v_pk_fma_f32 v[118:119], v[126:127], v[90:91], v[118:119]
	v_bfe_u32 v126, v116, 16, 1
	v_bfe_u32 v127, v117, 16, 1
	v_add3_u32 v116, v116, v126, s66
	v_add3_u32 v117, v117, v127, s66
	v_lshrrev_b32_e32 v122, 16, v116
	v_cvt_pk_bf16_f32 v114, v114, v115
	v_cvt_pk_bf16_f32 v116, v118, v119
	v_and_or_b32 v115, v117, s67, v122
	v_cvt_pk_bf16_f32 v117, v120, v121
	v_permlane16_swap_b32_e32 v114, v116
	s_nop 0
	v_permlane16_swap_b32_e32 v115, v117
	global_store_dwordx4 v[132:133], v[114:117], off offset:256
	s_nop 0
	v_lshlrev_b64 v[122:123], 11, v[136:137]
	v_lshl_add_u64 v[122:123], v[176:177], 0, v[122:123]
	v_lshl_add_u64 v[122:123], v[122:123], 0, v[130:131]
	s_waitcnt vmcnt(11)
	s_nop 1
	v_mov_b32_e32 v114, v242
	v_mov_b32_e32 v115, v243
	v_mov_b32_e32 v116, v244
	v_mov_b32_e32 v117, v245
	s_nop 1
	v_pk_fma_f32 v[84:85], v[84:85], v[108:109], v[116:117]
	v_pk_fma_f32 v[82:83], v[82:83], v[106:107], v[114:115]
	s_waitcnt vmcnt(10)
	s_nop 1
	v_mov_b32_e32 v118, v246
	v_mov_b32_e32 v119, v247
	v_mov_b32_e32 v120, v248
	v_mov_b32_e32 v121, v249
	s_nop 1
	v_pk_fma_f32 v[88:89], v[88:89], v[100:101], v[120:121]
	v_pk_fma_f32 v[86:87], v[86:87], v[98:99], v[118:119]
	v_bfe_u32 v118, v84, 16, 1
	v_bfe_u32 v120, v88, 16, 1
	v_bfe_u32 v119, v85, 16, 1
	v_bfe_u32 v121, v89, 16, 1
	v_add3_u32 v84, v84, v118, s66
	v_add3_u32 v88, v88, v120, s66
	v_add3_u32 v85, v85, v119, s66
	v_add3_u32 v89, v89, v121, s66
	v_lshrrev_b32_e32 v114, 16, v84
	v_lshrrev_b32_e32 v88, 16, v88
	v_cvt_pk_bf16_f32 v82, v82, v83
	v_cvt_pk_bf16_f32 v84, v86, v87
	v_and_or_b32 v83, v85, s67, v114
	v_and_or_b32 v85, v89, s67, v88
	v_permlane16_swap_b32_e32 v82, v84
	s_nop 0
	v_permlane16_swap_b32_e32 v83, v85
	global_store_dwordx4 v[122:123], v[82:85], off
	s_nop 0
	v_add_u32_e32 v114, 0xb0, v192
	v_ashrrev_i32_e32 v115, 31, v114
	v_lshlrev_b64 v[116:117], 12, v[114:115]
	v_lshl_add_u64 v[116:117], v[134:135], 0, v[116:117]
	v_lshlrev_b64 v[138:139], 10, v[114:115]
	s_waitcnt vmcnt(10)
	s_nop 1
	v_mov_b32_e32 v82, v210
	v_mov_b32_e32 v83, v211
	v_mov_b32_e32 v84, v212
	v_mov_b32_e32 v85, v213
	s_nop 1
	v_pk_fma_f32 v[84:85], v[104:105], v[96:97], v[84:85]
	v_pk_fma_f32 v[82:83], v[102:103], v[94:95], v[82:83]
	s_waitcnt vmcnt(9)
	s_nop 1
	v_mov_b32_e32 v86, v214
	v_mov_b32_e32 v87, v215
	v_mov_b32_e32 v88, v216
	v_mov_b32_e32 v89, v217
	s_nop 1
	v_pk_fma_f32 v[88:89], v[112:113], v[92:93], v[88:89]
	v_pk_fma_f32 v[86:87], v[110:111], v[90:91], v[86:87]
	v_bfe_u32 v104, v86, 16, 1
	v_bfe_u32 v110, v84, 16, 1
	v_bfe_u32 v112, v88, 16, 1
	v_bfe_u32 v105, v87, 16, 1
	v_bfe_u32 v111, v85, 16, 1
	v_bfe_u32 v113, v89, 16, 1
	v_add3_u32 v86, v86, v104, s66
	v_add3_u32 v84, v84, v110, s66
	v_add3_u32 v88, v88, v112, s66
	v_add3_u32 v87, v87, v105, s66
	v_add3_u32 v85, v85, v111, s66
	v_add3_u32 v89, v89, v113, s66
	v_lshrrev_b32_e32 v86, 16, v86
	v_lshrrev_b32_e32 v102, 16, v84
	v_lshrrev_b32_e32 v88, 16, v88
	v_cvt_pk_bf16_f32 v82, v82, v83
	v_and_or_b32 v84, v87, s67, v86
	v_and_or_b32 v83, v85, s67, v102
	v_and_or_b32 v85, v89, s67, v88
	v_permlane16_swap_b32_e32 v82, v84
	s_nop 0
	v_permlane16_swap_b32_e32 v83, v85
	global_store_dwordx4 v[122:123], v[82:85], off offset:256
	s_nop 0
	v_lshlrev_b64 v[102:103], 11, v[114:115]
	v_lshl_add_u64 v[102:103], v[176:177], 0, v[102:103]
	v_lshl_add_u64 v[102:103], v[102:103], 0, v[130:131]
	s_waitcnt vmcnt(8)
	s_nop 1
	v_mov_b32_e32 v82, v218
	v_mov_b32_e32 v83, v219
	v_mov_b32_e32 v84, v220
	v_mov_b32_e32 v85, v221
	s_nop 1
	v_pk_fma_f32 v[68:69], v[68:69], v[108:109], v[84:85]
	v_pk_fma_f32 v[66:67], v[66:67], v[106:107], v[82:83]
	s_waitcnt vmcnt(7)
	s_nop 1
	v_mov_b32_e32 v86, v222
	v_mov_b32_e32 v87, v223
	v_mov_b32_e32 v88, v224
	v_mov_b32_e32 v89, v225
	s_nop 1
	v_pk_fma_f32 v[72:73], v[72:73], v[100:101], v[88:89]
	v_pk_fma_f32 v[70:71], v[70:71], v[98:99], v[86:87]
	v_bfe_u32 v86, v68, 16, 1
	v_bfe_u32 v87, v69, 16, 1
	v_add3_u32 v68, v68, v86, s66
	v_add3_u32 v69, v69, v87, s66
	v_lshrrev_b32_e32 v82, 16, v68
	v_cvt_pk_bf16_f32 v66, v66, v67
	v_cvt_pk_bf16_f32 v68, v70, v71
	v_and_or_b32 v67, v69, s67, v82
	v_cvt_pk_bf16_f32 v69, v72, v73
	v_permlane16_swap_b32_e32 v66, v68
	s_nop 0
	v_permlane16_swap_b32_e32 v67, v69
	global_store_dwordx4 v[102:103], v[66:69], off
	s_nop 0
	s_waitcnt vmcnt(6)
	s_nop 1
	v_mov_b32_e32 v66, v226
	v_mov_b32_e32 v67, v227
	v_mov_b32_e32 v68, v228
	v_mov_b32_e32 v69, v229
	s_nop 1
	v_pk_fma_f32 v[68:69], v[76:77], v[96:97], v[68:69]
	v_pk_fma_f32 v[66:67], v[74:75], v[94:95], v[66:67]
	s_waitcnt vmcnt(5)
	s_nop 1
	v_mov_b32_e32 v70, v230
	v_mov_b32_e32 v71, v231
	v_mov_b32_e32 v72, v232
	v_mov_b32_e32 v73, v233
	s_nop 1
	v_pk_fma_f32 v[72:73], v[80:81], v[92:93], v[72:73]
	v_pk_fma_f32 v[70:71], v[78:79], v[90:91], v[70:71]
	v_cvt_pk_bf16_f32 v130, v66, v67
	v_cvt_pk_bf16_f32 v132, v70, v71
	v_cvt_pk_bf16_f32 v131, v68, v69
	v_cvt_pk_bf16_f32 v133, v72, v73
	v_permlane16_swap_b32_e32 v130, v132
	s_nop 0
	v_permlane16_swap_b32_e32 v131, v133
.LBB0_1086:
	s_andn2_b64 vcc, exec, s[30:31]
	s_cbranch_vccnz .LBB0_1088
	s_lshl_b32 s30, s72, 2
	s_or_b32 s31, s47, s30
	s_mul_i32 s31, s31, 0x18000
	s_add_i32 s31, s31, s45
	s_add_i32 s47, s31, 0x10000
	buffer_load_dwordx4 v[74:77], v193, s[8:11], s47 offen
	s_add_i32 s47, s31, 0x10400
	buffer_load_dwordx4 v[78:81], v193, s[8:11], s47 offen
	s_add_i32 s47, s31, 0x10800
	buffer_load_dwordx4 v[82:85], v193, s[8:11], s47 offen
	s_add_i32 s47, s31, 0x10c00
	buffer_load_dwordx4 v[86:89], v193, s[8:11], s47 offen
	s_add_i32 s47, s31, 0x11000
	buffer_load_dwordx4 v[90:93], v193, s[8:11], s47 offen
	s_add_i32 s47, s31, 0x11400
	buffer_load_dwordx4 v[94:97], v193, s[8:11], s47 offen
	s_add_i32 s47, s31, 0x11800
	s_add_i32 s31, s31, 0x11c00
	buffer_load_dwordx4 v[70:73], v193, s[8:11], s47 offen
	buffer_load_dwordx4 v[66:69], v193, s[8:11], s31 offen
	s_or_b32 s31, s30, s3
	s_mul_i32 s31, s31, 0x18000
	s_add_i32 s31, s31, s45
	s_add_i32 s47, s31, 0x38000
	s_add_i32 s3, s3, -1
	s_and_b32 s3, s3, 3
	s_or_b32 s3, s3, s30
	s_mul_i32 s3, s3, 0x18000
	s_add_i32 s3, s45, s3
	s_or_b32 s30, s3, 0x400
	v_and_b32_e32 v1, 1, v1
	v_cmp_eq_u32_e32 vcc, 0, v1
	s_waitcnt vmcnt(7)
	v_cvt_f32_f16_e32 v100, v76
	v_cvt_f32_f16_sdwa v101, v76 dst_sel:DWORD dst_unused:UNUSED_PAD src0_sel:WORD_1
	v_cvt_f32_f16_e32 v76, v77
	v_cvt_f32_f16_sdwa v77, v77 dst_sel:DWORD dst_unused:UNUSED_PAD src0_sel:WORD_1
	s_waitcnt vmcnt(6)
	v_cvt_f32_f16_e32 v102, v78
	v_cvt_f32_f16_sdwa v103, v78 dst_sel:DWORD dst_unused:UNUSED_PAD src0_sel:WORD_1
	v_cvt_f32_f16_e32 v78, v79
	v_cvt_f32_f16_sdwa v79, v79 dst_sel:DWORD dst_unused:UNUSED_PAD src0_sel:WORD_1
	v_cvt_f32_f16_e32 v104, v80
	v_cvt_f32_f16_sdwa v105, v80 dst_sel:DWORD dst_unused:UNUSED_PAD src0_sel:WORD_1
	v_cvt_f32_f16_e32 v80, v81
	v_cvt_f32_f16_sdwa v81, v81 dst_sel:DWORD dst_unused:UNUSED_PAD src0_sel:WORD_1
	s_waitcnt vmcnt(5)
	v_cvt_f32_f16_e32 v106, v82
	v_cvt_f32_f16_sdwa v107, v82 dst_sel:DWORD dst_unused:UNUSED_PAD src0_sel:WORD_1
	v_cvt_f32_f16_e32 v82, v83
	v_cvt_f32_f16_sdwa v83, v83 dst_sel:DWORD dst_unused:UNUSED_PAD src0_sel:WORD_1
	v_cvt_f32_f16_e32 v108, v84
	v_cvt_f32_f16_sdwa v109, v84 dst_sel:DWORD dst_unused:UNUSED_PAD src0_sel:WORD_1
	v_cvt_f32_f16_e32 v84, v85
	v_cvt_f32_f16_sdwa v85, v85 dst_sel:DWORD dst_unused:UNUSED_PAD src0_sel:WORD_1
	s_waitcnt vmcnt(4)
	v_cvt_f32_f16_e32 v110, v86
	v_cvt_f32_f16_sdwa v111, v86 dst_sel:DWORD dst_unused:UNUSED_PAD src0_sel:WORD_1
	v_cvt_f32_f16_e32 v86, v87
	v_cvt_f32_f16_sdwa v87, v87 dst_sel:DWORD dst_unused:UNUSED_PAD src0_sel:WORD_1
	v_cvt_f32_f16_e32 v112, v88
	v_cvt_f32_f16_sdwa v113, v88 dst_sel:DWORD dst_unused:UNUSED_PAD src0_sel:WORD_1
	v_cvt_f32_f16_e32 v88, v89
	v_cvt_f32_f16_sdwa v89, v89 dst_sel:DWORD dst_unused:UNUSED_PAD src0_sel:WORD_1
	s_waitcnt vmcnt(3)
	v_cvt_f32_f16_e32 v114, v90
	v_cvt_f32_f16_sdwa v115, v90 dst_sel:DWORD dst_unused:UNUSED_PAD src0_sel:WORD_1
	v_cvt_f32_f16_e32 v90, v91
	v_cvt_f32_f16_sdwa v91, v91 dst_sel:DWORD dst_unused:UNUSED_PAD src0_sel:WORD_1
	v_cvt_f32_f16_e32 v116, v92
	v_cvt_f32_f16_sdwa v117, v92 dst_sel:DWORD dst_unused:UNUSED_PAD src0_sel:WORD_1
	v_cvt_f32_f16_e32 v92, v93
	v_cvt_f32_f16_sdwa v93, v93 dst_sel:DWORD dst_unused:UNUSED_PAD src0_sel:WORD_1
	v_cvt_f32_f16_e32 v98, v74
	v_cvt_f32_f16_sdwa v99, v74 dst_sel:DWORD dst_unused:UNUSED_PAD src0_sel:WORD_1
	v_cvt_f32_f16_e32 v74, v75
	v_cvt_f32_f16_sdwa v75, v75 dst_sel:DWORD dst_unused:UNUSED_PAD src0_sel:WORD_1
	v_pk_add_f32 v[60:61], v[60:61], v[76:77]
	v_pk_add_f32 v[56:57], v[56:57], v[78:79]
	v_pk_add_f32 v[76:77], v[52:53], v[80:81]
	v_pk_add_f32 v[80:81], v[48:49], v[82:83]
	v_pk_add_f32 v[78:79], v[46:47], v[106:107]
	v_pk_add_f32 v[84:85], v[44:45], v[84:85]
	v_pk_add_f32 v[82:83], v[42:43], v[108:109]
	v_pk_add_f32 v[48:49], v[40:41], v[86:87]
	v_pk_add_f32 v[46:47], v[38:39], v[110:111]
	v_pk_add_f32 v[44:45], v[36:37], v[88:89]
	v_pk_add_f32 v[42:43], v[34:35], v[112:113]
	v_pk_add_f32 v[36:37], v[32:33], v[90:91]
	v_pk_add_f32 v[34:35], v[30:31], v[114:115]
	v_pk_add_f32 v[40:41], v[28:29], v[92:93]
	v_pk_add_f32 v[38:39], v[26:27], v[116:117]
	s_waitcnt vmcnt(1)
	v_cvt_f32_f16_e32 v26, v70
	v_cvt_f32_f16_sdwa v27, v70 dst_sel:DWORD dst_unused:UNUSED_PAD src0_sel:WORD_1
	v_cvt_f32_f16_e32 v28, v71
	v_cvt_f32_f16_sdwa v29, v71 dst_sel:DWORD dst_unused:UNUSED_PAD src0_sel:WORD_1
	v_cvt_f32_f16_e32 v30, v72
	v_cvt_f32_f16_e32 v32, v73
	v_cvt_f32_f16_sdwa v33, v73 dst_sel:DWORD dst_unused:UNUSED_PAD src0_sel:WORD_1
	v_cvt_f32_f16_sdwa v31, v72 dst_sel:DWORD dst_unused:UNUSED_PAD src0_sel:WORD_1
	v_pk_add_f32 v[64:65], v[64:65], v[74:75]
	v_pk_add_f32 v[62:63], v[62:63], v[98:99]
	v_pk_add_f32 v[58:59], v[58:59], v[100:101]
	v_cvt_f32_f16_e32 v118, v94
	v_cvt_f32_f16_sdwa v119, v94 dst_sel:DWORD dst_unused:UNUSED_PAD src0_sel:WORD_1
	v_cvt_f32_f16_e32 v94, v95
	v_cvt_f32_f16_sdwa v95, v95 dst_sel:DWORD dst_unused:UNUSED_PAD src0_sel:WORD_1
	v_cvt_f32_f16_e32 v120, v96
	v_cvt_f32_f16_sdwa v121, v96 dst_sel:DWORD dst_unused:UNUSED_PAD src0_sel:WORD_1
	v_cvt_f32_f16_e32 v96, v97
	v_cvt_f32_f16_sdwa v97, v97 dst_sel:DWORD dst_unused:UNUSED_PAD src0_sel:WORD_1
	v_pk_add_f32 v[54:55], v[54:55], v[102:103]
	v_pk_add_f32 v[74:75], v[50:51], v[104:105]
	v_pk_add_f32 v[16:17], v[16:17], v[28:29]
	v_pk_add_f32 v[14:15], v[14:15], v[26:27]
	v_pk_add_f32 v[12:13], v[12:13], v[32:33]
	v_pk_add_f32 v[10:11], v[10:11], v[30:31]
	s_waitcnt vmcnt(0)
	v_cvt_f32_f16_e32 v26, v66
	v_cvt_f32_f16_sdwa v27, v66 dst_sel:DWORD dst_unused:UNUSED_PAD src0_sel:WORD_1
	v_cvt_f32_f16_e32 v28, v67
	v_cvt_f32_f16_sdwa v29, v67 dst_sel:DWORD dst_unused:UNUSED_PAD src0_sel:WORD_1
	v_cvt_f32_f16_e32 v30, v68
	v_cvt_f32_f16_e32 v32, v69
	v_cvt_f32_f16_sdwa v33, v69 dst_sel:DWORD dst_unused:UNUSED_PAD src0_sel:WORD_1
	v_cvt_f32_f16_sdwa v31, v68 dst_sel:DWORD dst_unused:UNUSED_PAD src0_sel:WORD_1
	v_pk_add_f32 v[24:25], v[24:25], v[94:95]
	v_pk_add_f32 v[22:23], v[22:23], v[118:119]
	v_pk_add_f32 v[20:21], v[20:21], v[96:97]
	v_pk_add_f32 v[18:19], v[18:19], v[120:121]
	v_pk_add_f32 v[8:9], v[8:9], v[28:29]
	v_pk_add_f32 v[6:7], v[6:7], v[26:27]
	v_pk_add_f32 v[4:5], v[4:5], v[32:33]
	v_pk_add_f32 v[2:3], v[2:3], v[30:31]
	s_nop 0
	buffer_load_dwordx4 v[26:29], v193, s[8:11], s47 offen
	s_add_i32 s47, s31, 0x38400
	buffer_load_dwordx4 v[30:33], v193, s[8:11], s47 offen
	s_add_i32 s47, s31, 0x38800
	buffer_load_dwordx4 v[70:73], v193, s[8:11], s47 offen
	s_add_i32 s47, s31, 0x38c00
	buffer_load_dwordx4 v[88:91], v193, s[8:11], s47 offen
	s_add_i32 s47, s31, 0x39000
	buffer_load_dwordx4 v[98:101], v193, s[8:11], s47 offen
	s_add_i32 s47, s31, 0x39400
	buffer_load_dwordx4 v[102:105], v193, s[8:11], s47 offen
	s_add_i32 s47, s31, 0x39800
	s_add_i32 s31, s31, 0x39c00
	buffer_load_dwordx4 v[66:69], v193, s[8:11], s47 offen
	buffer_load_dwordx4 v[50:53], v193, s[8:11], s31 offen
	s_waitcnt vmcnt(7)
	v_cvt_f32_f16_e32 v86, v26
	v_cvt_f32_f16_sdwa v87, v26 dst_sel:DWORD dst_unused:UNUSED_PAD src0_sel:WORD_1
	s_waitcnt vmcnt(6)
	v_cvt_f32_f16_e32 v110, v30
	v_cvt_f32_f16_sdwa v111, v30 dst_sel:DWORD dst_unused:UNUSED_PAD src0_sel:WORD_1
	v_cvt_f32_f16_e32 v30, v31
	v_cvt_f32_f16_sdwa v31, v31 dst_sel:DWORD dst_unused:UNUSED_PAD src0_sel:WORD_1
	v_cvt_f32_f16_e32 v112, v32
	v_cvt_f32_f16_sdwa v113, v32 dst_sel:DWORD dst_unused:UNUSED_PAD src0_sel:WORD_1
	v_cvt_f32_f16_e32 v32, v33
	v_cvt_f32_f16_sdwa v33, v33 dst_sel:DWORD dst_unused:UNUSED_PAD src0_sel:WORD_1
	v_cvt_f32_f16_e32 v26, v27
	v_cvt_f32_f16_sdwa v27, v27 dst_sel:DWORD dst_unused:UNUSED_PAD src0_sel:WORD_1
	v_cvt_f32_f16_e32 v92, v28
	v_cvt_f32_f16_sdwa v93, v28 dst_sel:DWORD dst_unused:UNUSED_PAD src0_sel:WORD_1
	v_cvt_f32_f16_e32 v28, v29
	v_cvt_f32_f16_sdwa v29, v29 dst_sel:DWORD dst_unused:UNUSED_PAD src0_sel:WORD_1
	s_waitcnt vmcnt(4)
	v_cvt_f32_f16_e32 v118, v88
	v_cvt_f32_f16_sdwa v119, v88 dst_sel:DWORD dst_unused:UNUSED_PAD src0_sel:WORD_1
	v_cvt_f32_f16_e32 v120, v89
	v_cvt_f32_f16_sdwa v121, v89 dst_sel:DWORD dst_unused:UNUSED_PAD src0_sel:WORD_1
	v_pk_add_f32 v[88:89], v[56:57], v[30:31]
	v_pk_add_f32 v[56:57], v[76:77], v[32:33]
	v_cvt_f32_f16_e32 v30, v90
	v_cvt_f32_f16_e32 v32, v91
	v_cvt_f32_f16_sdwa v33, v91 dst_sel:DWORD dst_unused:UNUSED_PAD src0_sel:WORD_1
	v_cvt_f32_f16_sdwa v31, v90 dst_sel:DWORD dst_unused:UNUSED_PAD src0_sel:WORD_1
	v_pk_add_f32 v[108:109], v[64:65], v[26:27]
	v_pk_add_f32 v[96:97], v[60:61], v[28:29]
	v_pk_add_f32 v[28:29], v[48:49], v[120:121]
	v_pk_add_f32 v[26:27], v[46:47], v[118:119]
	v_pk_add_f32 v[32:33], v[44:45], v[32:33]
	v_pk_add_f32 v[30:31], v[42:43], v[30:31]
	s_waitcnt vmcnt(3)
	v_cvt_f32_f16_e32 v42, v98
	v_cvt_f32_f16_sdwa v43, v98 dst_sel:DWORD dst_unused:UNUSED_PAD src0_sel:WORD_1
	v_cvt_f32_f16_e32 v44, v99
	v_cvt_f32_f16_sdwa v45, v99 dst_sel:DWORD dst_unused:UNUSED_PAD src0_sel:WORD_1
	v_cvt_f32_f16_e32 v46, v100
	v_cvt_f32_f16_e32 v48, v101
	v_cvt_f32_f16_sdwa v49, v101 dst_sel:DWORD dst_unused:UNUSED_PAD src0_sel:WORD_1
	v_cvt_f32_f16_sdwa v47, v100 dst_sel:DWORD dst_unused:UNUSED_PAD src0_sel:WORD_1
	v_pk_add_f32 v[36:37], v[36:37], v[44:45]
	v_pk_add_f32 v[34:35], v[34:35], v[42:43]
	v_pk_add_f32 v[40:41], v[40:41], v[48:49]
	v_pk_add_f32 v[38:39], v[38:39], v[46:47]
	s_waitcnt vmcnt(2)
	v_cvt_f32_f16_e32 v42, v102
	v_cvt_f32_f16_sdwa v43, v102 dst_sel:DWORD dst_unused:UNUSED_PAD src0_sel:WORD_1
	v_cvt_f32_f16_e32 v44, v103
	v_cvt_f32_f16_sdwa v45, v103 dst_sel:DWORD dst_unused:UNUSED_PAD src0_sel:WORD_1
	v_cvt_f32_f16_e32 v46, v104
	v_cvt_f32_f16_e32 v48, v105
	v_cvt_f32_f16_sdwa v49, v105 dst_sel:DWORD dst_unused:UNUSED_PAD src0_sel:WORD_1
	v_cvt_f32_f16_sdwa v47, v104 dst_sel:DWORD dst_unused:UNUSED_PAD src0_sel:WORD_1
	v_cvt_f32_f16_e32 v114, v70
	v_cvt_f32_f16_sdwa v115, v70 dst_sel:DWORD dst_unused:UNUSED_PAD src0_sel:WORD_1
	v_cvt_f32_f16_e32 v70, v71
	v_cvt_f32_f16_sdwa v71, v71 dst_sel:DWORD dst_unused:UNUSED_PAD src0_sel:WORD_1
	v_cvt_f32_f16_e32 v116, v72
	v_cvt_f32_f16_sdwa v117, v72 dst_sel:DWORD dst_unused:UNUSED_PAD src0_sel:WORD_1
	v_cvt_f32_f16_e32 v72, v73
	v_cvt_f32_f16_sdwa v73, v73 dst_sel:DWORD dst_unused:UNUSED_PAD src0_sel:WORD_1
	v_pk_add_f32 v[44:45], v[24:25], v[44:45]
	v_pk_add_f32 v[42:43], v[22:23], v[42:43]
	v_pk_add_f32 v[48:49], v[20:21], v[48:49]
	v_pk_add_f32 v[46:47], v[18:19], v[46:47]
	s_waitcnt vmcnt(1)
	v_cvt_f32_f16_e32 v18, v66
	v_cvt_f32_f16_sdwa v19, v66 dst_sel:DWORD dst_unused:UNUSED_PAD src0_sel:WORD_1
	v_cvt_f32_f16_e32 v20, v67
	v_cvt_f32_f16_sdwa v21, v67 dst_sel:DWORD dst_unused:UNUSED_PAD src0_sel:WORD_1
	v_cvt_f32_f16_e32 v22, v68
	v_cvt_f32_f16_e32 v24, v69
	v_cvt_f32_f16_sdwa v25, v69 dst_sel:DWORD dst_unused:UNUSED_PAD src0_sel:WORD_1
	v_cvt_f32_f16_sdwa v23, v68 dst_sel:DWORD dst_unused:UNUSED_PAD src0_sel:WORD_1
	v_pk_add_f32 v[106:107], v[62:63], v[86:87]
	v_pk_add_f32 v[94:95], v[58:59], v[92:93]
	v_pk_add_f32 v[86:87], v[54:55], v[110:111]
	v_pk_add_f32 v[54:55], v[74:75], v[112:113]
	v_pk_add_f32 v[64:65], v[80:81], v[70:71]
	v_pk_add_f32 v[62:63], v[78:79], v[114:115]
	v_pk_add_f32 v[60:61], v[84:85], v[72:73]
	v_pk_add_f32 v[58:59], v[82:83], v[116:117]
	v_pk_add_f32 v[16:17], v[16:17], v[20:21]
	v_pk_add_f32 v[14:15], v[14:15], v[18:19]
	v_pk_add_f32 v[12:13], v[12:13], v[24:25]
	v_pk_add_f32 v[10:11], v[10:11], v[22:23]
	s_waitcnt vmcnt(0)
	v_cvt_f32_f16_e32 v18, v50
	v_cvt_f32_f16_sdwa v19, v50 dst_sel:DWORD dst_unused:UNUSED_PAD src0_sel:WORD_1
	v_cvt_f32_f16_e32 v20, v51
	v_cvt_f32_f16_sdwa v21, v51 dst_sel:DWORD dst_unused:UNUSED_PAD src0_sel:WORD_1
	v_cvt_f32_f16_e32 v22, v52
	v_cvt_f32_f16_e32 v24, v53
	v_cvt_f32_f16_sdwa v25, v53 dst_sel:DWORD dst_unused:UNUSED_PAD src0_sel:WORD_1
	v_cvt_f32_f16_sdwa v23, v52 dst_sel:DWORD dst_unused:UNUSED_PAD src0_sel:WORD_1
	v_pk_add_f32 v[72:73], v[8:9], v[20:21]
	v_pk_add_f32 v[70:71], v[6:7], v[18:19]
	v_pk_add_f32 v[76:77], v[4:5], v[24:25]
	v_pk_add_f32 v[74:75], v[2:3], v[22:23]
	s_nop 0
	buffer_load_dwordx4 v[2:5], v193, s[8:11], s3 offen
	buffer_load_dwordx4 v[6:9], v193, s[8:11], s30 offen
	s_or_b32 s30, s3, 0x800
	buffer_load_dwordx4 v[18:21], v193, s[8:11], s30 offen
	s_or_b32 s30, s3, 0xc00
	buffer_load_dwordx4 v[98:101], v193, s[8:11], s30 offen
	s_or_b32 s30, s3, 0x1000
	buffer_load_dwordx4 v[102:105], v193, s[8:11], s30 offen
	s_or_b32 s30, s3, 0x1400
	buffer_load_dwordx4 v[110:113], v193, s[8:11], s30 offen
	s_or_b32 s30, s3, 0x1800
	s_or_b32 s3, s3, 0x1c00
	buffer_load_dwordx4 v[90:93], v193, s[8:11], s30 offen
	buffer_load_dwordx4 v[82:85], v193, s[8:11], s3 offen
	v_ashrrev_i32_e32 v193, 31, v192
	s_waitcnt vmcnt(7)
	v_cvt_f32_f16_e32 v22, v2
	v_cvt_f32_f16_sdwa v23, v2 dst_sel:DWORD dst_unused:UNUSED_PAD src0_sel:WORD_1
	v_cvt_f32_f16_e32 v2, v3
	v_cvt_f32_f16_sdwa v3, v3 dst_sel:DWORD dst_unused:UNUSED_PAD src0_sel:WORD_1
	v_cvt_f32_f16_e32 v24, v4
	v_cvt_f32_f16_e32 v50, v5
	v_cvt_f32_f16_sdwa v51, v5 dst_sel:DWORD dst_unused:UNUSED_PAD src0_sel:WORD_1
	v_cvt_f32_f16_sdwa v25, v4 dst_sel:DWORD dst_unused:UNUSED_PAD src0_sel:WORD_1
	v_pk_add_f32 v[80:81], v[108:109], v[2:3]
	s_waitcnt vmcnt(6)
	v_cvt_f32_f16_e32 v2, v6
	v_cvt_f32_f16_sdwa v3, v6 dst_sel:DWORD dst_unused:UNUSED_PAD src0_sel:WORD_1
	v_cvt_f32_f16_e32 v4, v7
	v_cvt_f32_f16_sdwa v5, v7 dst_sel:DWORD dst_unused:UNUSED_PAD src0_sel:WORD_1
	v_cvt_f32_f16_e32 v6, v8
	v_cvt_f32_f16_sdwa v7, v8 dst_sel:DWORD dst_unused:UNUSED_PAD src0_sel:WORD_1
	v_pk_add_f32 v[78:79], v[106:107], v[22:23]
	v_pk_add_f32 v[68:69], v[96:97], v[50:51]
	v_cvt_f32_f16_e32 v22, v9
	v_cvt_f32_f16_sdwa v23, v9 dst_sel:DWORD dst_unused:UNUSED_PAD src0_sel:WORD_1
	v_pk_add_f32 v[52:53], v[88:89], v[4:5]
	v_pk_add_f32 v[50:51], v[86:87], v[2:3]
	v_pk_add_f32 v[54:55], v[54:55], v[6:7]
	s_waitcnt vmcnt(5)
	v_cvt_f32_f16_e32 v2, v18
	v_cvt_f32_f16_sdwa v3, v18 dst_sel:DWORD dst_unused:UNUSED_PAD src0_sel:WORD_1
	v_cvt_f32_f16_e32 v4, v19
	v_cvt_f32_f16_sdwa v5, v19 dst_sel:DWORD dst_unused:UNUSED_PAD src0_sel:WORD_1
	v_cvt_f32_f16_e32 v6, v20
	v_cvt_f32_f16_e32 v8, v21
	v_cvt_f32_f16_sdwa v9, v21 dst_sel:DWORD dst_unused:UNUSED_PAD src0_sel:WORD_1
	v_cvt_f32_f16_sdwa v7, v20 dst_sel:DWORD dst_unused:UNUSED_PAD src0_sel:WORD_1
	v_pk_add_f32 v[66:67], v[94:95], v[24:25]
	v_pk_add_f32 v[56:57], v[56:57], v[22:23]
	v_pk_add_f32 v[20:21], v[64:65], v[4:5]
	v_pk_add_f32 v[18:19], v[62:63], v[2:3]
	v_pk_add_f32 v[24:25], v[60:61], v[8:9]
	v_pk_add_f32 v[22:23], v[58:59], v[6:7]
	s_waitcnt vmcnt(4)
	v_cvt_f32_f16_e32 v2, v98
	v_cvt_f32_f16_sdwa v3, v98 dst_sel:DWORD dst_unused:UNUSED_PAD src0_sel:WORD_1
	v_cvt_f32_f16_e32 v4, v99
	v_cvt_f32_f16_sdwa v5, v99 dst_sel:DWORD dst_unused:UNUSED_PAD src0_sel:WORD_1
	v_cvt_f32_f16_e32 v6, v100
	v_cvt_f32_f16_e32 v8, v101
	v_cvt_f32_f16_sdwa v9, v101 dst_sel:DWORD dst_unused:UNUSED_PAD src0_sel:WORD_1
	v_cvt_f32_f16_sdwa v7, v100 dst_sel:DWORD dst_unused:UNUSED_PAD src0_sel:WORD_1
	v_pk_add_f32 v[4:5], v[28:29], v[4:5]
	v_pk_add_f32 v[2:3], v[26:27], v[2:3]
	v_pk_add_f32 v[8:9], v[32:33], v[8:9]
	v_pk_add_f32 v[6:7], v[30:31], v[6:7]
	s_waitcnt vmcnt(3)
	v_cvt_f32_f16_e32 v26, v102
	v_cvt_f32_f16_sdwa v27, v102 dst_sel:DWORD dst_unused:UNUSED_PAD src0_sel:WORD_1
	v_cvt_f32_f16_e32 v28, v103
	v_cvt_f32_f16_sdwa v29, v103 dst_sel:DWORD dst_unused:UNUSED_PAD src0_sel:WORD_1
	v_cvt_f32_f16_e32 v30, v104
	v_cvt_f32_f16_e32 v32, v105
	v_cvt_f32_f16_sdwa v33, v105 dst_sel:DWORD dst_unused:UNUSED_PAD src0_sel:WORD_1
	v_cvt_f32_f16_sdwa v31, v104 dst_sel:DWORD dst_unused:UNUSED_PAD src0_sel:WORD_1
	v_pk_add_f32 v[88:89], v[36:37], v[28:29]
	v_pk_add_f32 v[86:87], v[34:35], v[26:27]
	v_pk_add_f32 v[96:97], v[40:41], v[32:33]
	v_pk_add_f32 v[94:95], v[38:39], v[30:31]
	s_waitcnt vmcnt(2)
	v_cvt_f32_f16_e32 v26, v110
	v_cvt_f32_f16_sdwa v27, v110 dst_sel:DWORD dst_unused:UNUSED_PAD src0_sel:WORD_1
	v_cvt_f32_f16_e32 v28, v111
	v_cvt_f32_f16_sdwa v29, v111 dst_sel:DWORD dst_unused:UNUSED_PAD src0_sel:WORD_1
	v_cvt_f32_f16_e32 v30, v112
	v_cvt_f32_f16_e32 v32, v113
	v_cvt_f32_f16_sdwa v33, v113 dst_sel:DWORD dst_unused:UNUSED_PAD src0_sel:WORD_1
	v_cvt_f32_f16_sdwa v31, v112 dst_sel:DWORD dst_unused:UNUSED_PAD src0_sel:WORD_1
	v_pk_add_f32 v[60:61], v[44:45], v[28:29]
	v_pk_add_f32 v[58:59], v[42:43], v[26:27]
	v_pk_add_f32 v[64:65], v[48:49], v[32:33]
	v_pk_add_f32 v[62:63], v[46:47], v[30:31]
	s_waitcnt vmcnt(1)
	v_cvt_f32_f16_e32 v26, v90
	v_cvt_f32_f16_sdwa v27, v90 dst_sel:DWORD dst_unused:UNUSED_PAD src0_sel:WORD_1
	v_cvt_f32_f16_e32 v28, v91
	v_cvt_f32_f16_sdwa v29, v91 dst_sel:DWORD dst_unused:UNUSED_PAD src0_sel:WORD_1
	v_cvt_f32_f16_e32 v30, v92
	v_cvt_f32_f16_e32 v32, v93
	v_cvt_f32_f16_sdwa v33, v93 dst_sel:DWORD dst_unused:UNUSED_PAD src0_sel:WORD_1
	v_cvt_f32_f16_sdwa v31, v92 dst_sel:DWORD dst_unused:UNUSED_PAD src0_sel:WORD_1
	v_pk_add_f32 v[44:45], v[16:17], v[28:29]
	v_pk_add_f32 v[42:43], v[14:15], v[26:27]
	v_pk_add_f32 v[48:49], v[12:13], v[32:33]
	v_pk_add_f32 v[46:47], v[10:11], v[30:31]
	s_waitcnt vmcnt(0)
	v_cvt_f32_f16_e32 v10, v82
	v_cvt_f32_f16_sdwa v11, v82 dst_sel:DWORD dst_unused:UNUSED_PAD src0_sel:WORD_1
	v_cvt_f32_f16_e32 v12, v83
	v_cvt_f32_f16_sdwa v13, v83 dst_sel:DWORD dst_unused:UNUSED_PAD src0_sel:WORD_1
	v_cvt_f32_f16_e32 v14, v84
	v_cvt_f32_f16_e32 v16, v85
	v_cvt_f32_f16_sdwa v17, v85 dst_sel:DWORD dst_unused:UNUSED_PAD src0_sel:WORD_1
	v_cvt_f32_f16_sdwa v15, v84 dst_sel:DWORD dst_unused:UNUSED_PAD src0_sel:WORD_1
	v_pk_add_f32 v[12:13], v[72:73], v[12:13]
	v_pk_add_f32 v[10:11], v[70:71], v[10:11]
	v_pk_add_f32 v[16:17], v[76:77], v[16:17]
	v_pk_add_f32 v[14:15], v[74:75], v[14:15]
	v_lshl_add_u64 v[70:71], v[196:197], 2, s[12:13]
	v_lshlrev_b64 v[26:27], 12, v[192:193]
	v_lshl_add_u64 v[76:77], v[70:71], 0, v[26:27]
	global_load_dwordx4 v[38:41], v[194:195], off
	global_load_dwordx4 v[34:37], v[194:195], off offset:64
	global_load_dwordx4 v[30:33], v[194:195], off offset:512
	global_load_dwordx4 v[26:29], v[194:195], off offset:576
	s_mov_b64 s[78:79], 0x10000
	v_mov_b32_e32 v250, v76
	v_mov_b32_e32 v251, v77
	global_load_dwordx4 v[210:213], v[250:251], off
	global_load_dwordx4 v[214:217], v[250:251], off offset:64
	global_load_dwordx4 v[218:221], v[250:251], off offset:512
	global_load_dwordx4 v[222:225], v[250:251], off offset:576
	v_lshl_add_u64 v[250:251], v[250:251], 0, s[78:79]
	global_load_dwordx4 v[226:229], v[250:251], off
	global_load_dwordx4 v[230:233], v[250:251], off offset:64
	global_load_dwordx4 v[234:237], v[250:251], off offset:512
	global_load_dwordx4 v[238:241], v[250:251], off offset:576
	v_lshl_add_u64 v[250:251], v[250:251], 0, s[78:79]
	global_load_dwordx4 v[242:245], v[250:251], off
	global_load_dwordx4 v[246:249], v[250:251], off offset:64
	v_add_u32_e32 v90, 12, v209
	v_cndmask_b32_e32 v1, v90, v209, vcc
	v_add_u32_e32 v146, v1, v208
	v_ashrrev_i32_e32 v147, 31, v146
	s_waitcnt vmcnt(9)
	s_nop 1
	v_mov_b32_e32 v72, v210
	v_mov_b32_e32 v73, v211
	v_mov_b32_e32 v74, v212
	v_mov_b32_e32 v75, v213
	s_nop 1
	v_pk_fma_f32 v[72:73], v[78:79], v[38:39], v[72:73]
	s_nop 0
	s_waitcnt vmcnt(8)
	s_nop 1
	v_mov_b32_e32 v82, v214
	v_mov_b32_e32 v83, v215
	v_mov_b32_e32 v84, v216
	v_mov_b32_e32 v85, v217
	global_load_dwordx4 v[210:213], v[250:251], off offset:512
	global_load_dwordx4 v[214:217], v[250:251], off offset:576
	s_nop 1
	v_pk_fma_f32 v[66:67], v[66:67], v[34:35], v[82:83]
	v_cvt_pk_bf16_f32 v72, v72, v73
	v_pk_fma_f32 v[80:81], v[80:81], v[40:41], v[74:75]
	v_cvt_pk_bf16_f32 v74, v66, v67
	v_pk_fma_f32 v[68:69], v[68:69], v[36:37], v[84:85]
	v_cvt_pk_bf16_f32 v73, v80, v81
	v_cvt_pk_bf16_f32 v75, v68, v69
	v_lshlrev_b64 v[66:67], 11, v[192:193]
	v_lshl_add_u64 v[68:69], v[176:177], 0, v[66:67]
	v_lshlrev_b64 v[66:67], 1, v[146:147]
	v_permlane16_swap_b32_e32 v72, v74
	v_permlane16_swap_b32_e32 v73, v75
	v_lshl_add_u64 v[68:69], v[68:69], 0, v[66:67]
	global_store_dwordx4 v[68:69], v[72:75], off
	s_nop 0
	s_waitcnt vmcnt(10)
	s_nop 1
	v_mov_b32_e32 v72, v218
	v_mov_b32_e32 v73, v219
	v_mov_b32_e32 v74, v220
	v_mov_b32_e32 v75, v221
	s_nop 1
	v_pk_fma_f32 v[74:75], v[88:89], v[32:33], v[74:75]
	v_pk_fma_f32 v[72:73], v[86:87], v[30:31], v[72:73]
	s_waitcnt vmcnt(9)
	s_nop 1
	v_mov_b32_e32 v76, v222
	v_mov_b32_e32 v77, v223
	v_mov_b32_e32 v78, v224
	v_mov_b32_e32 v79, v225
	v_lshl_add_u64 v[250:251], v[250:251], 0, s[78:79]
	global_load_dwordx4 v[218:221], v[250:251], off
	global_load_dwordx4 v[222:225], v[250:251], off offset:64
	s_nop 1
	v_pk_fma_f32 v[78:79], v[96:97], v[28:29], v[78:79]
	v_pk_fma_f32 v[76:77], v[94:95], v[26:27], v[76:77]
	v_cvt_pk_bf16_f32 v72, v72, v73
	v_bfe_u32 v81, v76, 16, 1
	v_bfe_u32 v82, v77, 16, 1
	v_bfe_u32 v83, v74, 16, 1
	v_bfe_u32 v85, v78, 16, 1
	v_bfe_u32 v84, v75, 16, 1
	v_bfe_u32 v86, v79, 16, 1
	v_add3_u32 v73, v76, v81, s66
	v_add3_u32 v76, v77, v82, s66
	v_add3_u32 v74, v74, v83, s66
	v_add3_u32 v77, v78, v85, s66
	v_add3_u32 v75, v75, v84, s66
	v_add3_u32 v78, v79, v86, s66
	v_lshrrev_b32_e32 v73, 16, v73
	v_lshrrev_b32_e32 v79, 16, v74
	v_lshrrev_b32_e32 v77, 16, v77
	v_and_or_b32 v74, v76, s67, v73
	v_and_or_b32 v73, v75, s67, v79
	v_and_or_b32 v75, v78, s67, v77
	v_permlane16_swap_b32_e32 v72, v74
	s_nop 0
	v_permlane16_swap_b32_e32 v73, v75
	global_store_dwordx4 v[68:69], v[72:75], off offset:256
	v_add_u32_e32 v68, 16, v192
	v_ashrrev_i32_e32 v69, 31, v68
	v_lshlrev_b64 v[72:73], 12, v[68:69]
	v_lshl_add_u64 v[80:81], v[70:71], 0, v[72:73]
	v_lshlrev_b64 v[68:69], 11, v[68:69]
	v_lshl_add_u64 v[68:69], v[176:177], 0, v[68:69]
	v_lshl_add_u64 v[68:69], v[68:69], 0, v[66:67]
	s_waitcnt vmcnt(11)
	s_nop 1
	v_mov_b32_e32 v72, v226
	v_mov_b32_e32 v73, v227
	v_mov_b32_e32 v74, v228
	v_mov_b32_e32 v75, v229
	s_nop 1
	v_pk_fma_f32 v[52:53], v[52:53], v[40:41], v[74:75]
	v_pk_fma_f32 v[50:51], v[50:51], v[38:39], v[72:73]
	s_waitcnt vmcnt(10)
	s_nop 1
	v_mov_b32_e32 v76, v230
	v_mov_b32_e32 v77, v231
	v_mov_b32_e32 v78, v232
	v_mov_b32_e32 v79, v233
	global_load_dwordx4 v[226:229], v[250:251], off offset:512
	global_load_dwordx4 v[230:233], v[250:251], off offset:576
	s_nop 1
	v_pk_fma_f32 v[56:57], v[56:57], v[36:37], v[78:79]
	v_pk_fma_f32 v[54:55], v[54:55], v[34:35], v[76:77]
	v_cvt_pk_bf16_f32 v50, v50, v51
	v_bfe_u32 v73, v54, 16, 1
	v_bfe_u32 v74, v55, 16, 1
	v_bfe_u32 v75, v52, 16, 1
	v_bfe_u32 v77, v56, 16, 1
	v_bfe_u32 v76, v53, 16, 1
	v_bfe_u32 v78, v57, 16, 1
	v_add3_u32 v51, v54, v73, s66
	v_add3_u32 v54, v55, v74, s66
	v_add3_u32 v52, v52, v75, s66
	v_add3_u32 v55, v56, v77, s66
	v_add3_u32 v53, v53, v76, s66
	v_add3_u32 v56, v57, v78, s66
	v_lshrrev_b32_e32 v51, 16, v51
	v_lshrrev_b32_e32 v57, 16, v52
	v_lshrrev_b32_e32 v55, 16, v55
	v_and_or_b32 v52, v54, s67, v51
	v_and_or_b32 v51, v53, s67, v57
	v_and_or_b32 v53, v56, s67, v55
	v_permlane16_swap_b32_e32 v50, v52
	s_nop 0
	v_permlane16_swap_b32_e32 v51, v53
	global_store_dwordx4 v[68:69], v[50:53], off
	s_nop 0
	v_add_u32_e32 v72, 32, v192
	v_ashrrev_i32_e32 v73, 31, v72
	v_lshlrev_b64 v[74:75], 12, v[72:73]
	v_lshl_add_u64 v[74:75], v[70:71], 0, v[74:75]
	s_waitcnt vmcnt(12)
	s_nop 1
	v_mov_b32_e32 v50, v234
	v_mov_b32_e32 v51, v235
	v_mov_b32_e32 v52, v236
	v_mov_b32_e32 v53, v237
	s_nop 1
	v_pk_fma_f32 v[52:53], v[60:61], v[32:33], v[52:53]
	v_pk_fma_f32 v[50:51], v[58:59], v[30:31], v[50:51]
	s_waitcnt vmcnt(11)
	s_nop 1
	v_mov_b32_e32 v54, v238
	v_mov_b32_e32 v55, v239
	v_mov_b32_e32 v56, v240
	v_mov_b32_e32 v57, v241
	s_nop 1
	v_pk_fma_f32 v[56:57], v[64:65], v[28:29], v[56:57]
	v_pk_fma_f32 v[54:55], v[62:63], v[26:27], v[54:55]
	v_cvt_pk_bf16_f32 v50, v50, v51
	v_bfe_u32 v59, v54, 16, 1
	v_bfe_u32 v60, v55, 16, 1
	v_bfe_u32 v61, v52, 16, 1
	v_bfe_u32 v63, v56, 16, 1
	v_bfe_u32 v62, v53, 16, 1
	v_bfe_u32 v64, v57, 16, 1
	v_add3_u32 v51, v54, v59, s66
	v_add3_u32 v54, v55, v60, s66
	v_add3_u32 v52, v52, v61, s66
	v_add3_u32 v55, v56, v63, s66
	v_add3_u32 v53, v53, v62, s66
	v_add3_u32 v56, v57, v64, s66
	v_lshrrev_b32_e32 v51, 16, v51
	v_lshrrev_b32_e32 v57, 16, v52
	v_lshrrev_b32_e32 v55, 16, v55
	v_and_or_b32 v52, v54, s67, v51
	v_and_or_b32 v51, v53, s67, v57
	v_and_or_b32 v53, v56, s67, v55
	v_permlane16_swap_b32_e32 v50, v52
	s_nop 0
	v_permlane16_swap_b32_e32 v51, v53
	global_store_dwordx4 v[68:69], v[50:53], off offset:256
	s_nop 0
	v_lshlrev_b64 v[58:59], 11, v[72:73]
	v_lshl_add_u64 v[58:59], v[176:177], 0, v[58:59]
	v_lshl_add_u64 v[58:59], v[58:59], 0, v[66:67]
	s_waitcnt vmcnt(11)
	s_nop 1
	v_mov_b32_e32 v50, v242
	v_mov_b32_e32 v51, v243
	v_mov_b32_e32 v52, v244
	v_mov_b32_e32 v53, v245
	s_nop 1
	v_pk_fma_f32 v[20:21], v[20:21], v[40:41], v[52:53]
	v_pk_fma_f32 v[18:19], v[18:19], v[38:39], v[50:51]
	s_waitcnt vmcnt(10)
	s_nop 1
	v_mov_b32_e32 v54, v246
	v_mov_b32_e32 v55, v247
	v_mov_b32_e32 v56, v248
	v_mov_b32_e32 v57, v249
	s_nop 1
	v_pk_fma_f32 v[24:25], v[24:25], v[36:37], v[56:57]
	v_pk_fma_f32 v[22:23], v[22:23], v[34:35], v[54:55]
	v_cvt_pk_bf16_f32 v18, v18, v19
	v_bfe_u32 v51, v22, 16, 1
	v_bfe_u32 v52, v23, 16, 1
	v_bfe_u32 v53, v20, 16, 1
	v_bfe_u32 v55, v24, 16, 1
	v_bfe_u32 v54, v21, 16, 1
	v_bfe_u32 v56, v25, 16, 1
	v_add3_u32 v19, v22, v51, s66
	v_add3_u32 v22, v23, v52, s66
	v_add3_u32 v20, v20, v53, s66
	v_add3_u32 v23, v24, v55, s66
	v_add3_u32 v21, v21, v54, s66
	v_add3_u32 v24, v25, v56, s66
	v_lshrrev_b32_e32 v19, 16, v19
	v_lshrrev_b32_e32 v25, 16, v20
	v_lshrrev_b32_e32 v23, 16, v23
	v_and_or_b32 v20, v22, s67, v19
	v_and_or_b32 v19, v21, s67, v25
	v_and_or_b32 v21, v24, s67, v23
	v_permlane16_swap_b32_e32 v18, v20
	s_nop 0
	v_permlane16_swap_b32_e32 v19, v21
	global_store_dwordx4 v[58:59], v[18:21], off
	s_nop 0
	v_add_u32_e32 v50, 48, v192
	v_ashrrev_i32_e32 v51, 31, v50
	v_lshlrev_b64 v[52:53], 12, v[50:51]
	v_lshl_add_u64 v[52:53], v[70:71], 0, v[52:53]
	v_lshlrev_b64 v[138:139], 10, v[50:51]
	s_waitcnt vmcnt(10)
	s_nop 1
	v_mov_b32_e32 v18, v210
	v_mov_b32_e32 v19, v211
	v_mov_b32_e32 v20, v212
	v_mov_b32_e32 v21, v213
	s_nop 1
	v_pk_fma_f32 v[20:21], v[44:45], v[32:33], v[20:21]
	v_pk_fma_f32 v[18:19], v[42:43], v[30:31], v[18:19]
	s_waitcnt vmcnt(9)
	s_nop 1
	v_mov_b32_e32 v22, v214
	v_mov_b32_e32 v23, v215
	v_mov_b32_e32 v24, v216
	v_mov_b32_e32 v25, v217
	s_nop 1
	v_pk_fma_f32 v[24:25], v[48:49], v[28:29], v[24:25]
	v_pk_fma_f32 v[22:23], v[46:47], v[26:27], v[22:23]
	v_cvt_pk_bf16_f32 v18, v18, v19
	v_bfe_u32 v43, v22, 16, 1
	v_bfe_u32 v44, v23, 16, 1
	v_bfe_u32 v45, v20, 16, 1
	v_bfe_u32 v47, v24, 16, 1
	v_bfe_u32 v46, v21, 16, 1
	v_bfe_u32 v48, v25, 16, 1
	v_add3_u32 v19, v22, v43, s66
	v_add3_u32 v22, v23, v44, s66
	v_add3_u32 v20, v20, v45, s66
	v_add3_u32 v23, v24, v47, s66
	v_add3_u32 v21, v21, v46, s66
	v_add3_u32 v24, v25, v48, s66
	v_lshrrev_b32_e32 v19, 16, v19
	v_lshrrev_b32_e32 v25, 16, v20
	v_lshrrev_b32_e32 v23, 16, v23
	v_and_or_b32 v20, v22, s67, v19
	v_and_or_b32 v19, v21, s67, v25
	v_and_or_b32 v21, v24, s67, v23
	v_permlane16_swap_b32_e32 v18, v20
	s_nop 0
	v_permlane16_swap_b32_e32 v19, v21
	global_store_dwordx4 v[58:59], v[18:21], off offset:256
	s_nop 0
	v_lshlrev_b64 v[42:43], 11, v[50:51]
	v_lshl_add_u64 v[42:43], v[176:177], 0, v[42:43]
	v_lshl_add_u64 v[42:43], v[42:43], 0, v[66:67]
	s_waitcnt vmcnt(8)
	s_nop 1
	v_mov_b32_e32 v18, v218
	v_mov_b32_e32 v19, v219
	v_mov_b32_e32 v20, v220
	v_mov_b32_e32 v21, v221
	s_nop 1
	v_pk_fma_f32 v[4:5], v[4:5], v[40:41], v[20:21]
	v_pk_fma_f32 v[2:3], v[2:3], v[38:39], v[18:19]
	s_waitcnt vmcnt(7)
	s_nop 1
	v_mov_b32_e32 v22, v222
	v_mov_b32_e32 v23, v223
	v_mov_b32_e32 v24, v224
	v_mov_b32_e32 v25, v225
	s_nop 1
	v_pk_fma_f32 v[8:9], v[8:9], v[36:37], v[24:25]
	v_pk_fma_f32 v[6:7], v[6:7], v[34:35], v[22:23]
	v_cvt_pk_bf16_f32 v2, v2, v3
	v_bfe_u32 v19, v6, 16, 1
	v_bfe_u32 v20, v7, 16, 1
	v_bfe_u32 v21, v4, 16, 1
	v_bfe_u32 v23, v8, 16, 1
	v_bfe_u32 v22, v5, 16, 1
	v_bfe_u32 v24, v9, 16, 1
	v_add3_u32 v3, v6, v19, s66
	v_add3_u32 v6, v7, v20, s66
	v_add3_u32 v4, v4, v21, s66
	v_add3_u32 v7, v8, v23, s66
	v_add3_u32 v5, v5, v22, s66
	v_add3_u32 v8, v9, v24, s66
	v_lshrrev_b32_e32 v3, 16, v3
	v_lshrrev_b32_e32 v9, 16, v4
	v_lshrrev_b32_e32 v7, 16, v7
	v_and_or_b32 v4, v6, s67, v3
	v_and_or_b32 v3, v5, s67, v9
	v_and_or_b32 v5, v8, s67, v7
	v_permlane16_swap_b32_e32 v2, v4
	s_nop 0
	v_permlane16_swap_b32_e32 v3, v5
	global_store_dwordx4 v[42:43], v[2:5], off
	s_nop 0
	s_waitcnt vmcnt(6)
	s_nop 1
	v_mov_b32_e32 v2, v226
	v_mov_b32_e32 v3, v227
	v_mov_b32_e32 v4, v228
	v_mov_b32_e32 v5, v229
	s_nop 1
	v_pk_fma_f32 v[4:5], v[12:13], v[32:33], v[4:5]
	v_pk_fma_f32 v[2:3], v[10:11], v[30:31], v[2:3]
	s_waitcnt vmcnt(5)
	s_nop 1
	v_mov_b32_e32 v6, v230
	v_mov_b32_e32 v7, v231
	v_mov_b32_e32 v8, v232
	v_mov_b32_e32 v9, v233
	s_nop 1
	v_pk_fma_f32 v[8:9], v[16:17], v[28:29], v[8:9]
	v_pk_fma_f32 v[6:7], v[14:15], v[26:27], v[6:7]
	v_cvt_pk_bf16_f32 v130, v2, v3
	v_cvt_pk_bf16_f32 v132, v6, v7
	v_cvt_pk_bf16_f32 v131, v4, v5
	v_cvt_pk_bf16_f32 v133, v8, v9
	v_permlane16_swap_b32_e32 v130, v132
	s_nop 0
	v_permlane16_swap_b32_e32 v131, v133

.LBB0_1402:
	s_add_i32 s35, s63, 1
	s_cmp_gt_u32 s63, 1
	s_mov_b64 s[40:41], -1
	buffer_inv sc1
	s_cbranch_scc0 .LBB0_1404
	s_and_b32 s40, s35, 3
	s_lshl_b32 s37, s64, 2
	s_or_b32 s40, s40, s37
	s_mul_i32 s40, s40, 0x18000
	s_add_i32 s40, s40, s31
	s_add_i32 s41, s40, 0x10000
	buffer_load_dwordx4 v[136:139], v189, s[4:7], s41 offen
	s_add_i32 s41, s40, 0x10400
	buffer_load_dwordx4 v[140:143], v189, s[4:7], s41 offen
	s_add_i32 s41, s40, 0x10800
	buffer_load_dwordx4 v[144:147], v189, s[4:7], s41 offen
	s_add_i32 s41, s40, 0x10c00
	buffer_load_dwordx4 v[148:151], v189, s[4:7], s41 offen
	s_add_i32 s41, s40, 0x11000
	buffer_load_dwordx4 v[152:155], v189, s[4:7], s41 offen
	s_add_i32 s41, s40, 0x11400
	buffer_load_dwordx4 v[156:159], v189, s[4:7], s41 offen
	s_add_i32 s41, s40, 0x11800
	s_add_i32 s40, s40, 0x11c00
	buffer_load_dwordx4 v[132:135], v189, s[4:7], s41 offen
	buffer_load_dwordx4 v[128:131], v189, s[4:7], s40 offen
	s_or_b32 s40, s63, s37
	s_xor_b32 s40, s40, 2
	s_mul_i32 s40, s40, 0x18000
	s_add_i32 s40, s40, s31
	s_add_i32 s41, s40, 0x8000
	s_waitcnt vmcnt(7)
	v_cvt_f32_f16_e32 v202, v138
	v_cvt_f32_f16_sdwa v203, v138 dst_sel:DWORD dst_unused:UNUSED_PAD src0_sel:WORD_1
	v_cvt_f32_f16_e32 v138, v139
	v_cvt_f32_f16_sdwa v139, v139 dst_sel:DWORD dst_unused:UNUSED_PAD src0_sel:WORD_1
	s_waitcnt vmcnt(6)
	v_cvt_f32_f16_e32 v204, v140
	v_cvt_f32_f16_sdwa v205, v140 dst_sel:DWORD dst_unused:UNUSED_PAD src0_sel:WORD_1
	v_cvt_f32_f16_e32 v140, v141
	v_cvt_f32_f16_sdwa v141, v141 dst_sel:DWORD dst_unused:UNUSED_PAD src0_sel:WORD_1
	v_cvt_f32_f16_e32 v206, v142
	v_cvt_f32_f16_sdwa v207, v142 dst_sel:DWORD dst_unused:UNUSED_PAD src0_sel:WORD_1
	v_cvt_f32_f16_e32 v142, v143
	v_cvt_f32_f16_sdwa v143, v143 dst_sel:DWORD dst_unused:UNUSED_PAD src0_sel:WORD_1
	s_waitcnt vmcnt(5)
	v_cvt_f32_f16_e32 v210, v146
	v_cvt_f32_f16_sdwa v211, v146 dst_sel:DWORD dst_unused:UNUSED_PAD src0_sel:WORD_1
	v_cvt_f32_f16_e32 v212, v147
	v_cvt_f32_f16_sdwa v213, v147 dst_sel:DWORD dst_unused:UNUSED_PAD src0_sel:WORD_1
	s_waitcnt vmcnt(4)
	v_cvt_f32_f16_e32 v214, v148
	v_cvt_f32_f16_sdwa v215, v148 dst_sel:DWORD dst_unused:UNUSED_PAD src0_sel:WORD_1
	v_cvt_f32_f16_e32 v148, v149
	v_cvt_f32_f16_sdwa v149, v149 dst_sel:DWORD dst_unused:UNUSED_PAD src0_sel:WORD_1
	v_cvt_f32_f16_e32 v216, v150
	v_cvt_f32_f16_sdwa v217, v150 dst_sel:DWORD dst_unused:UNUSED_PAD src0_sel:WORD_1
	v_cvt_f32_f16_e32 v150, v151
	v_cvt_f32_f16_sdwa v151, v151 dst_sel:DWORD dst_unused:UNUSED_PAD src0_sel:WORD_1
	s_waitcnt vmcnt(3)
	v_cvt_f32_f16_e32 v218, v152
	v_cvt_f32_f16_sdwa v219, v152 dst_sel:DWORD dst_unused:UNUSED_PAD src0_sel:WORD_1
	v_cvt_f32_f16_e32 v152, v153
	v_cvt_f32_f16_sdwa v153, v153 dst_sel:DWORD dst_unused:UNUSED_PAD src0_sel:WORD_1
	v_cvt_f32_f16_e32 v220, v154
	v_cvt_f32_f16_sdwa v221, v154 dst_sel:DWORD dst_unused:UNUSED_PAD src0_sel:WORD_1
	v_cvt_f32_f16_e32 v154, v155
	v_cvt_f32_f16_sdwa v155, v155 dst_sel:DWORD dst_unused:UNUSED_PAD src0_sel:WORD_1
	v_cvt_f32_f16_e32 v200, v136
	v_cvt_f32_f16_sdwa v201, v136 dst_sel:DWORD dst_unused:UNUSED_PAD src0_sel:WORD_1
	v_cvt_f32_f16_e32 v136, v137
	v_cvt_f32_f16_sdwa v137, v137 dst_sel:DWORD dst_unused:UNUSED_PAD src0_sel:WORD_1
	v_cvt_f32_f16_e32 v208, v144
	v_cvt_f32_f16_sdwa v209, v144 dst_sel:DWORD dst_unused:UNUSED_PAD src0_sel:WORD_1
	v_cvt_f32_f16_e32 v144, v145
	v_cvt_f32_f16_sdwa v145, v145 dst_sel:DWORD dst_unused:UNUSED_PAD src0_sel:WORD_1
	s_waitcnt vmcnt(2)
	v_cvt_f32_f16_e32 v222, v156
	v_cvt_f32_f16_sdwa v223, v156 dst_sel:DWORD dst_unused:UNUSED_PAD src0_sel:WORD_1
	v_cvt_f32_f16_e32 v224, v157
	v_cvt_f32_f16_sdwa v225, v157 dst_sel:DWORD dst_unused:UNUSED_PAD src0_sel:WORD_1
	v_cvt_f32_f16_e32 v226, v158
	v_cvt_f32_f16_sdwa v227, v158 dst_sel:DWORD dst_unused:UNUSED_PAD src0_sel:WORD_1
	v_cvt_f32_f16_e32 v228, v159
	v_cvt_f32_f16_sdwa v229, v159 dst_sel:DWORD dst_unused:UNUSED_PAD src0_sel:WORD_1
	v_pk_add_f32 v[122:123], v[122:123], v[138:139]
	v_pk_add_f32 v[138:139], v[118:119], v[140:141]
	v_pk_add_f32 v[142:143], v[114:115], v[142:143]
	v_pk_add_f32 v[140:141], v[112:113], v[206:207]
	v_pk_add_f32 v[158:159], v[106:107], v[212:213]
	v_pk_add_f32 v[156:157], v[104:105], v[210:211]
	v_pk_add_f32 v[114:115], v[102:103], v[148:149]
	v_pk_add_f32 v[112:113], v[100:101], v[214:215]
	v_pk_add_f32 v[106:107], v[98:99], v[150:151]
	v_pk_add_f32 v[104:105], v[96:97], v[216:217]
	v_pk_add_f32 v[102:103], v[94:95], v[152:153]
	v_pk_add_f32 v[100:101], v[92:93], v[218:219]
	v_pk_add_f32 v[98:99], v[90:91], v[154:155]
	v_pk_add_f32 v[96:97], v[88:89], v[220:221]
	s_waitcnt vmcnt(1)
	v_cvt_f32_f16_e32 v88, v132
	v_cvt_f32_f16_sdwa v89, v132 dst_sel:DWORD dst_unused:UNUSED_PAD src0_sel:WORD_1
	v_cvt_f32_f16_e32 v90, v133
	v_cvt_f32_f16_sdwa v91, v133 dst_sel:DWORD dst_unused:UNUSED_PAD src0_sel:WORD_1
	v_cvt_f32_f16_e32 v92, v134
	v_cvt_f32_f16_e32 v94, v135
	v_cvt_f32_f16_sdwa v95, v135 dst_sel:DWORD dst_unused:UNUSED_PAD src0_sel:WORD_1
	v_cvt_f32_f16_sdwa v93, v134 dst_sel:DWORD dst_unused:UNUSED_PAD src0_sel:WORD_1
	v_pk_add_f32 v[126:127], v[126:127], v[136:137]
	v_pk_add_f32 v[124:125], v[124:125], v[200:201]
	v_pk_add_f32 v[120:121], v[120:121], v[202:203]
	v_pk_add_f32 v[136:137], v[116:117], v[204:205]
	v_pk_add_f32 v[146:147], v[110:111], v[144:145]
	v_pk_add_f32 v[144:145], v[108:109], v[208:209]
	v_pk_add_f32 v[78:79], v[78:79], v[90:91]
	v_pk_add_f32 v[76:77], v[76:77], v[88:89]
	v_pk_add_f32 v[74:75], v[74:75], v[94:95]
	v_pk_add_f32 v[72:73], v[72:73], v[92:93]
	s_waitcnt vmcnt(0)
	v_cvt_f32_f16_e32 v88, v128
	v_cvt_f32_f16_sdwa v89, v128 dst_sel:DWORD dst_unused:UNUSED_PAD src0_sel:WORD_1
	v_cvt_f32_f16_e32 v90, v129
	v_cvt_f32_f16_sdwa v91, v129 dst_sel:DWORD dst_unused:UNUSED_PAD src0_sel:WORD_1
	v_cvt_f32_f16_e32 v92, v130
	v_cvt_f32_f16_e32 v94, v131
	v_cvt_f32_f16_sdwa v95, v131 dst_sel:DWORD dst_unused:UNUSED_PAD src0_sel:WORD_1
	v_cvt_f32_f16_sdwa v93, v130 dst_sel:DWORD dst_unused:UNUSED_PAD src0_sel:WORD_1
	v_pk_add_f32 v[86:87], v[86:87], v[224:225]
	v_pk_add_f32 v[84:85], v[84:85], v[222:223]
	v_pk_add_f32 v[82:83], v[82:83], v[228:229]
	v_pk_add_f32 v[80:81], v[80:81], v[226:227]
	v_pk_add_f32 v[70:71], v[70:71], v[90:91]
	v_pk_add_f32 v[68:69], v[68:69], v[88:89]
	v_pk_add_f32 v[66:67], v[66:67], v[94:95]
	v_pk_add_f32 v[64:65], v[64:65], v[92:93]
	s_nop 0
	buffer_load_dwordx4 v[88:91], v189, s[4:7], s41 offen
	s_add_i32 s41, s40, 0x8400
	buffer_load_dwordx4 v[92:95], v189, s[4:7], s41 offen
	s_add_i32 s41, s40, 0x8800
	buffer_load_dwordx4 v[128:131], v189, s[4:7], s41 offen
	s_add_i32 s41, s40, 0x8c00
	buffer_load_dwordx4 v[200:203], v189, s[4:7], s41 offen
	s_add_i32 s41, s40, 0x9000
	buffer_load_dwordx4 v[204:207], v189, s[4:7], s41 offen
	s_add_i32 s41, s40, 0x9400
	buffer_load_dwordx4 v[208:211], v189, s[4:7], s41 offen
	s_add_i32 s41, s40, 0x9800
	s_add_i32 s40, s40, 0x9c00
	buffer_load_dwordx4 v[116:119], v189, s[4:7], s41 offen
	buffer_load_dwordx4 v[108:111], v189, s[4:7], s40 offen
	s_add_i32 s40, s63, -1
	s_and_b32 s40, s40, 3
	s_or_b32 s37, s40, s37
	s_mul_i32 s37, s37, 0x18000
	s_add_i32 s37, s31, s37
	s_or_b32 s40, s37, 0x400
	s_waitcnt vmcnt(7)
	v_cvt_f32_f16_e32 v132, v88
	v_cvt_f32_f16_sdwa v133, v88 dst_sel:DWORD dst_unused:UNUSED_PAD src0_sel:WORD_1
	v_cvt_f32_f16_e32 v88, v89
	v_cvt_f32_f16_sdwa v89, v89 dst_sel:DWORD dst_unused:UNUSED_PAD src0_sel:WORD_1
	s_waitcnt vmcnt(6)
	v_cvt_f32_f16_e32 v150, v92
	v_cvt_f32_f16_sdwa v151, v92 dst_sel:DWORD dst_unused:UNUSED_PAD src0_sel:WORD_1
	v_cvt_f32_f16_e32 v92, v93
	v_cvt_f32_f16_sdwa v93, v93 dst_sel:DWORD dst_unused:UNUSED_PAD src0_sel:WORD_1
	v_cvt_f32_f16_e32 v212, v94
	v_cvt_f32_f16_sdwa v213, v94 dst_sel:DWORD dst_unused:UNUSED_PAD src0_sel:WORD_1
	v_cvt_f32_f16_e32 v94, v95
	v_cvt_f32_f16_sdwa v95, v95 dst_sel:DWORD dst_unused:UNUSED_PAD src0_sel:WORD_1
	v_cvt_f32_f16_e32 v148, v90
	v_cvt_f32_f16_sdwa v149, v90 dst_sel:DWORD dst_unused:UNUSED_PAD src0_sel:WORD_1
	v_cvt_f32_f16_e32 v90, v91
	v_cvt_f32_f16_sdwa v91, v91 dst_sel:DWORD dst_unused:UNUSED_PAD src0_sel:WORD_1
	s_waitcnt vmcnt(4)
	v_cvt_f32_f16_e32 v220, v200
	v_cvt_f32_f16_sdwa v221, v200 dst_sel:DWORD dst_unused:UNUSED_PAD src0_sel:WORD_1
	v_pk_add_f32 v[134:135], v[126:127], v[88:89]
	v_pk_add_f32 v[154:155], v[138:139], v[92:93]
	v_pk_add_f32 v[152:153], v[136:137], v[150:151]
	v_pk_add_f32 v[150:151], v[142:143], v[94:95]
	v_cvt_f32_f16_e32 v88, v201
	v_cvt_f32_f16_sdwa v89, v201 dst_sel:DWORD dst_unused:UNUSED_PAD src0_sel:WORD_1
	v_cvt_f32_f16_e32 v92, v202
	v_cvt_f32_f16_e32 v94, v203
	v_cvt_f32_f16_sdwa v95, v203 dst_sel:DWORD dst_unused:UNUSED_PAD src0_sel:WORD_1
	v_cvt_f32_f16_sdwa v93, v202 dst_sel:DWORD dst_unused:UNUSED_PAD src0_sel:WORD_1
	v_pk_add_f32 v[126:127], v[122:123], v[90:91]
	v_pk_add_f32 v[90:91], v[114:115], v[88:89]
	v_pk_add_f32 v[88:89], v[112:113], v[220:221]
	v_pk_add_f32 v[94:95], v[106:107], v[94:95]
	v_pk_add_f32 v[92:93], v[104:105], v[92:93]
	s_waitcnt vmcnt(3)
	v_cvt_f32_f16_e32 v104, v204
	v_cvt_f32_f16_sdwa v105, v204 dst_sel:DWORD dst_unused:UNUSED_PAD src0_sel:WORD_1
	v_cvt_f32_f16_e32 v106, v205
	v_cvt_f32_f16_sdwa v107, v205 dst_sel:DWORD dst_unused:UNUSED_PAD src0_sel:WORD_1
	v_cvt_f32_f16_e32 v112, v206
	v_cvt_f32_f16_e32 v114, v207
	v_cvt_f32_f16_sdwa v115, v207 dst_sel:DWORD dst_unused:UNUSED_PAD src0_sel:WORD_1
	v_cvt_f32_f16_sdwa v113, v206 dst_sel:DWORD dst_unused:UNUSED_PAD src0_sel:WORD_1
	v_pk_add_f32 v[102:103], v[102:103], v[106:107]
	v_pk_add_f32 v[100:101], v[100:101], v[104:105]
	v_pk_add_f32 v[106:107], v[98:99], v[114:115]
	v_pk_add_f32 v[104:105], v[96:97], v[112:113]
	s_waitcnt vmcnt(2)
	v_cvt_f32_f16_e32 v96, v208
	v_cvt_f32_f16_sdwa v97, v208 dst_sel:DWORD dst_unused:UNUSED_PAD src0_sel:WORD_1
	v_cvt_f32_f16_e32 v98, v209
	v_cvt_f32_f16_sdwa v99, v209 dst_sel:DWORD dst_unused:UNUSED_PAD src0_sel:WORD_1
	v_cvt_f32_f16_e32 v214, v128
	v_cvt_f32_f16_sdwa v215, v128 dst_sel:DWORD dst_unused:UNUSED_PAD src0_sel:WORD_1
	v_cvt_f32_f16_e32 v128, v129
	v_cvt_f32_f16_sdwa v129, v129 dst_sel:DWORD dst_unused:UNUSED_PAD src0_sel:WORD_1
	v_cvt_f32_f16_e32 v216, v130
	v_cvt_f32_f16_sdwa v217, v130 dst_sel:DWORD dst_unused:UNUSED_PAD src0_sel:WORD_1
	v_cvt_f32_f16_e32 v218, v131
	v_cvt_f32_f16_sdwa v219, v131 dst_sel:DWORD dst_unused:UNUSED_PAD src0_sel:WORD_1
	v_cvt_f32_f16_e32 v112, v210
	v_cvt_f32_f16_e32 v114, v211
	v_cvt_f32_f16_sdwa v115, v211 dst_sel:DWORD dst_unused:UNUSED_PAD src0_sel:WORD_1
	v_cvt_f32_f16_sdwa v113, v210 dst_sel:DWORD dst_unused:UNUSED_PAD src0_sel:WORD_1
	v_pk_add_f32 v[86:87], v[86:87], v[98:99]
	v_pk_add_f32 v[84:85], v[84:85], v[96:97]
	s_waitcnt vmcnt(1)
	v_cvt_f32_f16_e32 v96, v116
	v_cvt_f32_f16_sdwa v97, v116 dst_sel:DWORD dst_unused:UNUSED_PAD src0_sel:WORD_1
	v_cvt_f32_f16_e32 v98, v117
	v_cvt_f32_f16_sdwa v99, v117 dst_sel:DWORD dst_unused:UNUSED_PAD src0_sel:WORD_1
	v_cvt_f32_f16_e32 v116, v118
	v_cvt_f32_f16_e32 v136, v119
	v_cvt_f32_f16_sdwa v137, v119 dst_sel:DWORD dst_unused:UNUSED_PAD src0_sel:WORD_1
	v_cvt_f32_f16_sdwa v117, v118 dst_sel:DWORD dst_unused:UNUSED_PAD src0_sel:WORD_1
	v_pk_add_f32 v[132:133], v[124:125], v[132:133]
	v_pk_add_f32 v[124:125], v[120:121], v[148:149]
	v_pk_add_f32 v[148:149], v[140:141], v[212:213]
	v_pk_add_f32 v[130:131], v[146:147], v[128:129]
	v_pk_add_f32 v[128:129], v[144:145], v[214:215]
	v_pk_add_f32 v[122:123], v[158:159], v[218:219]
	v_pk_add_f32 v[120:121], v[156:157], v[216:217]
	v_pk_add_f32 v[82:83], v[82:83], v[114:115]
	v_pk_add_f32 v[80:81], v[80:81], v[112:113]
	v_pk_add_f32 v[114:115], v[78:79], v[98:99]
	v_pk_add_f32 v[112:113], v[76:77], v[96:97]
	v_pk_add_f32 v[118:119], v[74:75], v[136:137]
	v_pk_add_f32 v[116:117], v[72:73], v[116:117]
	s_waitcnt vmcnt(0)
	v_cvt_f32_f16_e32 v72, v108
	v_cvt_f32_f16_sdwa v73, v108 dst_sel:DWORD dst_unused:UNUSED_PAD src0_sel:WORD_1
	v_cvt_f32_f16_e32 v74, v109
	v_cvt_f32_f16_sdwa v75, v109 dst_sel:DWORD dst_unused:UNUSED_PAD src0_sel:WORD_1
	v_cvt_f32_f16_e32 v76, v110
	v_cvt_f32_f16_e32 v78, v111
	v_cvt_f32_f16_sdwa v79, v111 dst_sel:DWORD dst_unused:UNUSED_PAD src0_sel:WORD_1
	v_cvt_f32_f16_sdwa v77, v110 dst_sel:DWORD dst_unused:UNUSED_PAD src0_sel:WORD_1
	v_pk_add_f32 v[138:139], v[70:71], v[74:75]
	v_pk_add_f32 v[136:137], v[68:69], v[72:73]
	v_pk_add_f32 v[142:143], v[66:67], v[78:79]
	v_pk_add_f32 v[140:141], v[64:65], v[76:77]
	s_nop 0
	buffer_load_dwordx4 v[64:67], v189, s[4:7], s37 offen
	buffer_load_dwordx4 v[68:71], v189, s[4:7], s40 offen
	s_or_b32 s40, s37, 0x800
	buffer_load_dwordx4 v[72:75], v189, s[4:7], s40 offen
	s_or_b32 s40, s37, 0xc00
	buffer_load_dwordx4 v[200:203], v189, s[4:7], s40 offen
	s_or_b32 s40, s37, 0x1000
	buffer_load_dwordx4 v[204:207], v189, s[4:7], s40 offen
	s_or_b32 s40, s37, 0x1400
	buffer_load_dwordx4 v[208:211], v189, s[4:7], s40 offen
	s_or_b32 s40, s37, 0x1800
	s_or_b32 s37, s37, 0x1c00
	buffer_load_dwordx4 v[156:159], v189, s[4:7], s40 offen
	buffer_load_dwordx4 v[144:147], v189, s[4:7], s37 offen
	s_mov_b64 s[40:41], 0
	s_waitcnt vmcnt(7)
	v_cvt_f32_f16_e32 v76, v64
	v_cvt_f32_f16_sdwa v77, v64 dst_sel:DWORD dst_unused:UNUSED_PAD src0_sel:WORD_1
	v_cvt_f32_f16_e32 v64, v65
	v_cvt_f32_f16_sdwa v65, v65 dst_sel:DWORD dst_unused:UNUSED_PAD src0_sel:WORD_1
	v_cvt_f32_f16_e32 v78, v66
	v_cvt_f32_f16_e32 v96, v67
	v_cvt_f32_f16_sdwa v97, v67 dst_sel:DWORD dst_unused:UNUSED_PAD src0_sel:WORD_1
	v_cvt_f32_f16_sdwa v79, v66 dst_sel:DWORD dst_unused:UNUSED_PAD src0_sel:WORD_1
	v_pk_add_f32 v[134:135], v[134:135], v[64:65]
	s_waitcnt vmcnt(6)
	v_cvt_f32_f16_e32 v64, v68
	v_cvt_f32_f16_sdwa v65, v68 dst_sel:DWORD dst_unused:UNUSED_PAD src0_sel:WORD_1
	v_cvt_f32_f16_e32 v66, v69
	v_cvt_f32_f16_sdwa v67, v69 dst_sel:DWORD dst_unused:UNUSED_PAD src0_sel:WORD_1
	v_cvt_f32_f16_e32 v68, v70
	v_cvt_f32_f16_sdwa v69, v70 dst_sel:DWORD dst_unused:UNUSED_PAD src0_sel:WORD_1
	v_pk_add_f32 v[132:133], v[132:133], v[76:77]
	v_pk_add_f32 v[126:127], v[126:127], v[96:97]
	v_cvt_f32_f16_e32 v76, v71
	v_cvt_f32_f16_sdwa v77, v71 dst_sel:DWORD dst_unused:UNUSED_PAD src0_sel:WORD_1
	v_pk_add_f32 v[108:109], v[152:153], v[64:65]
	v_pk_add_f32 v[96:97], v[148:149], v[68:69]
	s_waitcnt vmcnt(5)
	v_cvt_f32_f16_e32 v64, v72
	v_cvt_f32_f16_sdwa v65, v72 dst_sel:DWORD dst_unused:UNUSED_PAD src0_sel:WORD_1
	v_cvt_f32_f16_e32 v68, v74
	v_cvt_f32_f16_sdwa v69, v74 dst_sel:DWORD dst_unused:UNUSED_PAD src0_sel:WORD_1
	v_pk_add_f32 v[110:111], v[154:155], v[66:67]
	v_cvt_f32_f16_e32 v66, v73
	v_cvt_f32_f16_sdwa v67, v73 dst_sel:DWORD dst_unused:UNUSED_PAD src0_sel:WORD_1
	v_cvt_f32_f16_e32 v70, v75
	v_cvt_f32_f16_sdwa v71, v75 dst_sel:DWORD dst_unused:UNUSED_PAD src0_sel:WORD_1
	v_pk_add_f32 v[98:99], v[150:151], v[76:77]
	v_pk_add_f32 v[76:77], v[128:129], v[64:65]
	v_pk_add_f32 v[72:73], v[120:121], v[68:69]
	s_waitcnt vmcnt(4)
	v_cvt_f32_f16_e32 v64, v200
	v_cvt_f32_f16_sdwa v65, v200 dst_sel:DWORD dst_unused:UNUSED_PAD src0_sel:WORD_1
	v_cvt_f32_f16_e32 v120, v202
	v_cvt_f32_f16_sdwa v121, v202 dst_sel:DWORD dst_unused:UNUSED_PAD src0_sel:WORD_1
	v_pk_add_f32 v[124:125], v[124:125], v[78:79]
	v_pk_add_f32 v[78:79], v[130:131], v[66:67]
	v_pk_add_f32 v[74:75], v[122:123], v[70:71]
	v_cvt_f32_f16_e32 v66, v201
	v_cvt_f32_f16_sdwa v67, v201 dst_sel:DWORD dst_unused:UNUSED_PAD src0_sel:WORD_1
	v_cvt_f32_f16_e32 v122, v203
	v_cvt_f32_f16_sdwa v123, v203 dst_sel:DWORD dst_unused:UNUSED_PAD src0_sel:WORD_1
	v_pk_add_f32 v[68:69], v[88:89], v[64:65]
	v_pk_add_f32 v[64:65], v[92:93], v[120:121]
	s_waitcnt vmcnt(3)
	v_cvt_f32_f16_e32 v92, v206
	v_cvt_f32_f16_sdwa v93, v206 dst_sel:DWORD dst_unused:UNUSED_PAD src0_sel:WORD_1
	v_pk_add_f32 v[70:71], v[90:91], v[66:67]
	v_pk_add_f32 v[66:67], v[94:95], v[122:123]
	v_cvt_f32_f16_e32 v94, v207
	v_cvt_f32_f16_sdwa v95, v207 dst_sel:DWORD dst_unused:UNUSED_PAD src0_sel:WORD_1
	v_cvt_f32_f16_e32 v88, v204
	v_cvt_f32_f16_sdwa v89, v204 dst_sel:DWORD dst_unused:UNUSED_PAD src0_sel:WORD_1
	v_pk_add_f32 v[152:153], v[104:105], v[92:93]
	s_waitcnt vmcnt(2)
	v_cvt_f32_f16_e32 v92, v210
	v_cvt_f32_f16_sdwa v93, v210 dst_sel:DWORD dst_unused:UNUSED_PAD src0_sel:WORD_1
	v_cvt_f32_f16_e32 v90, v205
	v_cvt_f32_f16_sdwa v91, v205 dst_sel:DWORD dst_unused:UNUSED_PAD src0_sel:WORD_1
	v_pk_add_f32 v[154:155], v[106:107], v[94:95]
	v_cvt_f32_f16_e32 v94, v211
	v_cvt_f32_f16_sdwa v95, v211 dst_sel:DWORD dst_unused:UNUSED_PAD src0_sel:WORD_1
	v_pk_add_f32 v[148:149], v[100:101], v[88:89]
	v_cvt_f32_f16_e32 v88, v208
	v_cvt_f32_f16_sdwa v89, v208 dst_sel:DWORD dst_unused:UNUSED_PAD src0_sel:WORD_1
	v_pk_add_f32 v[128:129], v[80:81], v[92:93]
	s_waitcnt vmcnt(1)
	v_cvt_f32_f16_e32 v80, v156
	v_cvt_f32_f16_sdwa v81, v156 dst_sel:DWORD dst_unused:UNUSED_PAD src0_sel:WORD_1
	v_pk_add_f32 v[150:151], v[102:103], v[90:91]
	v_cvt_f32_f16_e32 v90, v209
	v_cvt_f32_f16_sdwa v91, v209 dst_sel:DWORD dst_unused:UNUSED_PAD src0_sel:WORD_1
	v_pk_add_f32 v[130:131], v[82:83], v[94:95]
	v_cvt_f32_f16_e32 v82, v157
	v_cvt_f32_f16_sdwa v83, v157 dst_sel:DWORD dst_unused:UNUSED_PAD src0_sel:WORD_1
	v_pk_add_f32 v[120:121], v[84:85], v[88:89]
	v_cvt_f32_f16_e32 v84, v158
	v_cvt_f32_f16_sdwa v85, v158 dst_sel:DWORD dst_unused:UNUSED_PAD src0_sel:WORD_1
	v_pk_add_f32 v[100:101], v[112:113], v[80:81]
	s_waitcnt vmcnt(0)
	v_cvt_f32_f16_e32 v80, v144
	v_cvt_f32_f16_sdwa v81, v144 dst_sel:DWORD dst_unused:UNUSED_PAD src0_sel:WORD_1
	v_cvt_f32_f16_e32 v88, v146
	v_cvt_f32_f16_sdwa v89, v146 dst_sel:DWORD dst_unused:UNUSED_PAD src0_sel:WORD_1
	v_pk_add_f32 v[122:123], v[86:87], v[90:91]
	v_cvt_f32_f16_e32 v86, v159
	v_cvt_f32_f16_sdwa v87, v159 dst_sel:DWORD dst_unused:UNUSED_PAD src0_sel:WORD_1
	v_pk_add_f32 v[102:103], v[114:115], v[82:83]
	v_cvt_f32_f16_e32 v82, v145
	v_cvt_f32_f16_sdwa v83, v145 dst_sel:DWORD dst_unused:UNUSED_PAD src0_sel:WORD_1
	v_cvt_f32_f16_e32 v90, v147
	v_cvt_f32_f16_sdwa v91, v147 dst_sel:DWORD dst_unused:UNUSED_PAD src0_sel:WORD_1
	v_pk_add_f32 v[104:105], v[116:117], v[84:85]
	v_pk_add_f32 v[84:85], v[136:137], v[80:81]
	v_pk_add_f32 v[80:81], v[140:141], v[88:89]
	v_and_b32_e32 v88, 1, v197
	v_add_u32_e32 v89, 12, v199
	v_cmp_eq_u32_e32 vcc, 0, v88
	v_pk_add_f32 v[106:107], v[118:119], v[86:87]
	v_pk_add_f32 v[86:87], v[138:139], v[82:83]
	v_pk_add_f32 v[82:83], v[142:143], v[90:91]
	v_cndmask_b32_e32 v88, v89, v199, vcc
	v_add_u32_e32 v142, 0x80, v188
	v_add_u32_e32 v88, v88, v198
	v_ashrrev_i32_e32 v143, 31, v142
	v_ashrrev_i32_e32 v89, 31, v88
	v_lshlrev_b64 v[90:91], 11, v[142:143]
	v_lshl_add_u64 v[90:91], v[170:171], 0, v[90:91]
	v_lshlrev_b64 v[136:137], 1, v[88:89]
	v_lshl_add_u64 v[144:145], v[90:91], 0, v[136:137]
	global_load_dwordx4 v[116:119], v[190:191], off
	global_load_dwordx4 v[112:115], v[190:191], off offset:64
	global_load_dwordx4 v[92:95], v[190:191], off offset:512
	global_load_dwordx4 v[88:91], v[190:191], off offset:576
	s_mov_b64 s[78:79], 0x8000
	v_mov_b32_e32 v250, v144
	v_mov_b32_e32 v251, v145
	global_load_dwordx4 v[200:203], v[250:251], off
	global_load_dwordx4 v[204:207], v[250:251], off offset:256
	v_lshl_add_u64 v[250:251], v[250:251], 0, s[78:79]
	global_load_dwordx4 v[208:211], v[250:251], off
	global_load_dwordx4 v[212:215], v[250:251], off offset:256
	v_lshl_add_u64 v[250:251], v[250:251], 0, s[78:79]
	global_load_dwordx4 v[216:219], v[250:251], off
	s_waitcnt vmcnt(4)
	s_nop 1
	v_mov_b32_e32 v138, v200
	v_mov_b32_e32 v139, v201
	v_mov_b32_e32 v140, v202
	v_mov_b32_e32 v141, v203
	global_load_dwordx4 v[200:203], v[250:251], off offset:256
	s_nop 1
	v_permlane16_swap_b32_e32 v138, v140
	v_permlane16_swap_b32_e32 v139, v141
	v_lshlrev_b32_e32 v146, 16, v138
	v_and_b32_e32 v147, 0xffff0000, v138
	v_lshlrev_b32_e32 v138, 16, v139
	v_and_b32_e32 v139, 0xffff0000, v139
	v_lshlrev_b32_e32 v156, 16, v140
	v_and_b32_e32 v157, 0xffff0000, v140
	v_lshlrev_b32_e32 v158, 16, v141
	v_and_b32_e32 v159, 0xffff0000, v141
	v_pk_fma_f32 v[140:141], v[134:135], v[118:119], v[138:139]
	v_pk_fma_f32 v[138:139], v[132:133], v[116:117], v[146:147]
	v_lshlrev_b64 v[132:133], 12, v[142:143]
	v_lshl_add_u64 v[134:135], s[0:1], 0, v[132:133]
	v_lshlrev_b64 v[132:133], 2, v[186:187]
	v_lshl_add_u64 v[134:135], v[134:135], 0, v[132:133]
	v_pk_fma_f32 v[126:127], v[126:127], v[114:115], v[158:159]
	v_pk_fma_f32 v[124:125], v[124:125], v[112:113], v[156:157]
	global_store_dwordx4 v[134:135], v[138:141], off
	global_store_dwordx4 v[134:135], v[124:127], off offset:64
	v_add_u32_e32 v142, 0x90, v188
	v_ashrrev_i32_e32 v143, 31, v142
	v_lshlrev_b64 v[138:139], 11, v[142:143]
	v_lshl_add_u64 v[138:139], v[170:171], 0, v[138:139]
	v_lshl_add_u64 v[144:145], v[138:139], 0, v[136:137]
	s_waitcnt vmcnt(6)
	s_nop 1
	v_mov_b32_e32 v124, v204
	v_mov_b32_e32 v125, v205
	v_mov_b32_e32 v126, v206
	v_mov_b32_e32 v127, v207
	v_lshl_add_u64 v[250:251], v[250:251], 0, s[78:79]
	global_load_dwordx4 v[204:207], v[250:251], off
	s_nop 1
	v_permlane16_swap_b32_e32 v124, v126
	v_permlane16_swap_b32_e32 v125, v127
	v_lshlrev_b32_e32 v138, 16, v124
	v_and_b32_e32 v139, 0xffff0000, v124
	v_lshlrev_b32_e32 v124, 16, v125
	v_and_b32_e32 v125, 0xffff0000, v125
	v_lshlrev_b32_e32 v146, 16, v126
	v_and_b32_e32 v147, 0xffff0000, v126
	v_lshlrev_b32_e32 v140, 16, v127
	v_and_b32_e32 v141, 0xffff0000, v127
	v_pk_fma_f32 v[126:127], v[150:151], v[94:95], v[124:125]
	v_pk_fma_f32 v[124:125], v[148:149], v[92:93], v[138:139]
	v_pk_fma_f32 v[140:141], v[154:155], v[90:91], v[140:141]
	v_pk_fma_f32 v[138:139], v[152:153], v[88:89], v[146:147]
	global_store_dwordx4 v[134:135], v[124:127], off offset:512
	global_store_dwordx4 v[134:135], v[138:141], off offset:576
	v_lshlrev_b64 v[134:135], 12, v[142:143]
	v_lshl_add_u64 v[134:135], s[0:1], 0, v[134:135]
	v_lshl_add_u64 v[134:135], v[134:135], 0, v[132:133]
	s_waitcnt vmcnt(8)
	s_nop 1
	v_mov_b32_e32 v124, v208
	v_mov_b32_e32 v125, v209
	v_mov_b32_e32 v126, v210
	v_mov_b32_e32 v127, v211
	global_load_dwordx4 v[208:211], v[250:251], off offset:256
	s_nop 1
	v_mov_b32_e32 v139, v126
	v_mov_b32_e32 v141, v127
	s_nop 0
	v_permlane16_swap_b32_e32 v124, v139
	v_permlane16_swap_b32_e32 v125, v141
	v_lshlrev_b32_e32 v126, 16, v124
	v_and_b32_e32 v127, 0xffff0000, v124
	v_lshlrev_b32_e32 v124, 16, v125
	v_and_b32_e32 v125, 0xffff0000, v125
	v_lshlrev_b32_e32 v138, 16, v139
	v_and_b32_e32 v139, 0xffff0000, v139
	v_lshlrev_b32_e32 v140, 16, v141
	v_and_b32_e32 v141, 0xffff0000, v141
	v_pk_fma_f32 v[110:111], v[110:111], v[118:119], v[124:125]
	v_pk_fma_f32 v[108:109], v[108:109], v[116:117], v[126:127]
	v_pk_fma_f32 v[98:99], v[98:99], v[114:115], v[140:141]
	v_pk_fma_f32 v[96:97], v[96:97], v[112:113], v[138:139]
	global_store_dwordx4 v[134:135], v[108:111], off
	global_store_dwordx4 v[134:135], v[96:99], off offset:64
	v_add_u32_e32 v124, 0xa0, v188
	v_ashrrev_i32_e32 v125, 31, v124
	v_lshlrev_b64 v[108:109], 11, v[124:125]
	v_lshl_add_u64 v[108:109], v[170:171], 0, v[108:109]
	v_lshl_add_u64 v[126:127], v[108:109], 0, v[136:137]
	s_waitcnt vmcnt(10)
	s_nop 1
	v_mov_b32_e32 v96, v212
	v_mov_b32_e32 v97, v213
	v_mov_b32_e32 v98, v214
	v_mov_b32_e32 v99, v215
	s_nop 1
	v_permlane16_swap_b32_e32 v96, v98
	v_permlane16_swap_b32_e32 v97, v99
	v_lshlrev_b32_e32 v108, 16, v96
	v_and_b32_e32 v109, 0xffff0000, v96
	v_lshlrev_b32_e32 v96, 16, v97
	v_and_b32_e32 v97, 0xffff0000, v97
	v_lshlrev_b32_e32 v138, 16, v98
	v_and_b32_e32 v139, 0xffff0000, v98
	v_lshlrev_b32_e32 v110, 16, v99
	v_and_b32_e32 v111, 0xffff0000, v99
	v_pk_fma_f32 v[98:99], v[122:123], v[94:95], v[96:97]
	v_pk_fma_f32 v[96:97], v[120:121], v[92:93], v[108:109]
	v_pk_fma_f32 v[110:111], v[130:131], v[90:91], v[110:111]
	v_pk_fma_f32 v[108:109], v[128:129], v[88:89], v[138:139]
	global_store_dwordx4 v[134:135], v[96:99], off offset:512
	global_store_dwordx4 v[134:135], v[108:111], off offset:576
	s_waitcnt vmcnt(11)
	s_nop 1
	v_mov_b32_e32 v96, v216
	v_mov_b32_e32 v97, v217
	v_mov_b32_e32 v98, v218
	v_mov_b32_e32 v99, v219
	s_nop 1
	v_mov_b32_e32 v121, v99
	v_mov_b32_e32 v111, v98
	v_lshlrev_b64 v[108:109], 12, v[124:125]
	s_nop 0
	v_permlane16_swap_b32_e32 v96, v111
	v_permlane16_swap_b32_e32 v97, v121
	v_lshl_add_u64 v[108:109], s[0:1], 0, v[108:109]
	v_lshlrev_b32_e32 v98, 16, v96
	v_and_b32_e32 v99, 0xffff0000, v96
	v_lshlrev_b32_e32 v96, 16, v97
	v_and_b32_e32 v97, 0xffff0000, v97
	v_lshl_add_u64 v[108:109], v[108:109], 0, v[132:133]
	v_lshlrev_b32_e32 v110, 16, v111
	v_and_b32_e32 v111, 0xffff0000, v111
	v_lshlrev_b32_e32 v120, 16, v121
	v_and_b32_e32 v121, 0xffff0000, v121
	v_pk_fma_f32 v[78:79], v[78:79], v[118:119], v[96:97]
	v_pk_fma_f32 v[76:77], v[76:77], v[116:117], v[98:99]
	v_pk_fma_f32 v[74:75], v[74:75], v[114:115], v[120:121]
	v_pk_fma_f32 v[72:73], v[72:73], v[112:113], v[110:111]
	global_store_dwordx4 v[108:109], v[76:79], off
	global_store_dwordx4 v[108:109], v[72:75], off offset:64
	v_add_u32_e32 v96, 0xb0, v188
	v_ashrrev_i32_e32 v97, 31, v96
	v_lshlrev_b64 v[76:77], 11, v[96:97]
	v_lshl_add_u64 v[76:77], v[170:171], 0, v[76:77]
	v_lshl_add_u64 v[98:99], v[76:77], 0, v[136:137]
	v_lshlrev_b64 v[136:137], 10, v[96:97]
	s_waitcnt vmcnt(12)
	s_nop 1
	v_mov_b32_e32 v72, v200
	v_mov_b32_e32 v73, v201
	v_mov_b32_e32 v74, v202
	v_mov_b32_e32 v75, v203
	s_nop 1
	v_permlane16_swap_b32_e32 v72, v74
	v_permlane16_swap_b32_e32 v73, v75
	v_lshlrev_b32_e32 v76, 16, v72
	v_and_b32_e32 v77, 0xffff0000, v72
	v_lshlrev_b32_e32 v72, 16, v73
	v_and_b32_e32 v73, 0xffff0000, v73
	v_lshlrev_b32_e32 v110, 16, v74
	v_and_b32_e32 v111, 0xffff0000, v74
	v_lshlrev_b32_e32 v78, 16, v75
	v_and_b32_e32 v79, 0xffff0000, v75
	v_pk_fma_f32 v[74:75], v[102:103], v[94:95], v[72:73]
	v_pk_fma_f32 v[72:73], v[100:101], v[92:93], v[76:77]
	v_pk_fma_f32 v[78:79], v[106:107], v[90:91], v[78:79]
	v_pk_fma_f32 v[76:77], v[104:105], v[88:89], v[110:111]
	global_store_dwordx4 v[108:109], v[72:75], off offset:512
	global_store_dwordx4 v[108:109], v[76:79], off offset:576
	s_waitcnt vmcnt(11)
	s_nop 1
	v_mov_b32_e32 v72, v204
	v_mov_b32_e32 v73, v205
	v_mov_b32_e32 v74, v206
	v_mov_b32_e32 v75, v207
	s_nop 1
	v_mov_b32_e32 v101, v75
	v_mov_b32_e32 v79, v74
	v_lshlrev_b64 v[76:77], 12, v[96:97]
	s_nop 0
	v_permlane16_swap_b32_e32 v72, v79
	v_permlane16_swap_b32_e32 v73, v101
	v_lshl_add_u64 v[76:77], s[0:1], 0, v[76:77]
	v_lshlrev_b32_e32 v74, 16, v72
	v_and_b32_e32 v75, 0xffff0000, v72
	v_lshlrev_b32_e32 v72, 16, v73
	v_and_b32_e32 v73, 0xffff0000, v73
	v_lshl_add_u64 v[76:77], v[76:77], 0, v[132:133]
	v_lshlrev_b32_e32 v78, 16, v79
	v_and_b32_e32 v79, 0xffff0000, v79
	v_lshlrev_b32_e32 v100, 16, v101
	v_and_b32_e32 v101, 0xffff0000, v101
	v_pk_fma_f32 v[70:71], v[70:71], v[118:119], v[72:73]
	v_pk_fma_f32 v[68:69], v[68:69], v[116:117], v[74:75]
	v_pk_fma_f32 v[66:67], v[66:67], v[114:115], v[100:101]
	v_pk_fma_f32 v[64:65], v[64:65], v[112:113], v[78:79]
	global_store_dwordx4 v[76:77], v[68:71], off
	global_store_dwordx4 v[76:77], v[64:67], off offset:64
	s_waitcnt vmcnt(10)
	s_nop 1
	v_mov_b32_e32 v64, v208
	v_mov_b32_e32 v65, v209
	v_mov_b32_e32 v66, v210
	v_mov_b32_e32 v67, v211
	s_nop 1
	v_permlane16_swap_b32_e32 v64, v66
	v_permlane16_swap_b32_e32 v65, v67
	v_lshlrev_b32_e32 v68, 16, v64
	v_and_b32_e32 v69, 0xffff0000, v64
	v_lshlrev_b32_e32 v64, 16, v65
	v_and_b32_e32 v65, 0xffff0000, v65
	v_lshlrev_b32_e32 v70, 16, v66
	v_and_b32_e32 v71, 0xffff0000, v66
	v_lshlrev_b32_e32 v72, 16, v67
	v_and_b32_e32 v73, 0xffff0000, v67
	v_pk_fma_f32 v[66:67], v[86:87], v[94:95], v[64:65]
	v_pk_fma_f32 v[64:65], v[84:85], v[92:93], v[68:69]
	v_pk_fma_f32 v[130:131], v[82:83], v[90:91], v[72:73]
	v_pk_fma_f32 v[128:129], v[80:81], v[88:89], v[70:71]
	global_store_dwordx4 v[76:77], v[64:67], off offset:512
.LBB0_1404:
	s_andn2_b64 vcc, exec, s[40:41]
	s_cbranch_vccnz .LBB0_1406
	s_lshl_b32 s37, s64, 2
	s_or_b32 s35, s35, s37
	s_mul_i32 s35, s35, 0x18000
	s_add_i32 s35, s35, s31
	s_add_i32 s40, s35, 0x10000
	buffer_load_dwordx4 v[72:75], v189, s[4:7], s40 offen
	s_add_i32 s40, s35, 0x10400
	buffer_load_dwordx4 v[76:79], v189, s[4:7], s40 offen
	s_add_i32 s40, s35, 0x10800
	buffer_load_dwordx4 v[80:83], v189, s[4:7], s40 offen
	s_add_i32 s40, s35, 0x10c00
	buffer_load_dwordx4 v[84:87], v189, s[4:7], s40 offen
	s_add_i32 s40, s35, 0x11000
	buffer_load_dwordx4 v[88:91], v189, s[4:7], s40 offen
	s_add_i32 s40, s35, 0x11400
	buffer_load_dwordx4 v[92:95], v189, s[4:7], s40 offen
	s_add_i32 s40, s35, 0x11800
	s_add_i32 s35, s35, 0x11c00
	buffer_load_dwordx4 v[68:71], v189, s[4:7], s40 offen
	buffer_load_dwordx4 v[64:67], v189, s[4:7], s35 offen
	s_or_b32 s35, s37, s63
	s_mul_i32 s35, s35, 0x18000
	s_add_i32 s35, s35, s31
	s_add_i32 s40, s35, 0x38000
	s_add_i32 s63, s63, -1
	s_waitcnt vmcnt(7)
	v_cvt_f32_f16_e32 v98, v74
	v_cvt_f32_f16_sdwa v99, v74 dst_sel:DWORD dst_unused:UNUSED_PAD src0_sel:WORD_1
	v_cvt_f32_f16_e32 v74, v75
	v_cvt_f32_f16_sdwa v75, v75 dst_sel:DWORD dst_unused:UNUSED_PAD src0_sel:WORD_1
	s_waitcnt vmcnt(6)
	v_cvt_f32_f16_e32 v100, v76
	v_cvt_f32_f16_sdwa v101, v76 dst_sel:DWORD dst_unused:UNUSED_PAD src0_sel:WORD_1
	v_cvt_f32_f16_e32 v76, v77
	v_cvt_f32_f16_sdwa v77, v77 dst_sel:DWORD dst_unused:UNUSED_PAD src0_sel:WORD_1
	v_cvt_f32_f16_e32 v102, v78
	v_cvt_f32_f16_sdwa v103, v78 dst_sel:DWORD dst_unused:UNUSED_PAD src0_sel:WORD_1
	v_cvt_f32_f16_e32 v78, v79
	v_cvt_f32_f16_sdwa v79, v79 dst_sel:DWORD dst_unused:UNUSED_PAD src0_sel:WORD_1
	s_waitcnt vmcnt(5)
	v_cvt_f32_f16_e32 v106, v82
	v_cvt_f32_f16_sdwa v107, v82 dst_sel:DWORD dst_unused:UNUSED_PAD src0_sel:WORD_1
	v_cvt_f32_f16_e32 v108, v83
	v_cvt_f32_f16_sdwa v109, v83 dst_sel:DWORD dst_unused:UNUSED_PAD src0_sel:WORD_1
	s_waitcnt vmcnt(4)
	v_cvt_f32_f16_e32 v110, v84
	v_cvt_f32_f16_sdwa v111, v84 dst_sel:DWORD dst_unused:UNUSED_PAD src0_sel:WORD_1
	v_cvt_f32_f16_e32 v84, v85
	v_cvt_f32_f16_sdwa v85, v85 dst_sel:DWORD dst_unused:UNUSED_PAD src0_sel:WORD_1
	v_cvt_f32_f16_e32 v112, v86
	v_cvt_f32_f16_sdwa v113, v86 dst_sel:DWORD dst_unused:UNUSED_PAD src0_sel:WORD_1
	v_cvt_f32_f16_e32 v86, v87
	v_cvt_f32_f16_sdwa v87, v87 dst_sel:DWORD dst_unused:UNUSED_PAD src0_sel:WORD_1
	s_waitcnt vmcnt(3)
	v_cvt_f32_f16_e32 v114, v88
	v_cvt_f32_f16_sdwa v115, v88 dst_sel:DWORD dst_unused:UNUSED_PAD src0_sel:WORD_1
	v_cvt_f32_f16_e32 v88, v89
	v_cvt_f32_f16_sdwa v89, v89 dst_sel:DWORD dst_unused:UNUSED_PAD src0_sel:WORD_1
	v_cvt_f32_f16_e32 v116, v90
	v_cvt_f32_f16_sdwa v117, v90 dst_sel:DWORD dst_unused:UNUSED_PAD src0_sel:WORD_1
	v_cvt_f32_f16_e32 v90, v91
	v_cvt_f32_f16_sdwa v91, v91 dst_sel:DWORD dst_unused:UNUSED_PAD src0_sel:WORD_1
	v_cvt_f32_f16_e32 v96, v72
	v_cvt_f32_f16_sdwa v97, v72 dst_sel:DWORD dst_unused:UNUSED_PAD src0_sel:WORD_1
	v_cvt_f32_f16_e32 v72, v73
	v_cvt_f32_f16_sdwa v73, v73 dst_sel:DWORD dst_unused:UNUSED_PAD src0_sel:WORD_1
	v_cvt_f32_f16_e32 v104, v80
	v_cvt_f32_f16_sdwa v105, v80 dst_sel:DWORD dst_unused:UNUSED_PAD src0_sel:WORD_1
	v_cvt_f32_f16_e32 v80, v81
	v_cvt_f32_f16_sdwa v81, v81 dst_sel:DWORD dst_unused:UNUSED_PAD src0_sel:WORD_1
	s_waitcnt vmcnt(2)
	v_cvt_f32_f16_e32 v118, v92
	v_cvt_f32_f16_sdwa v119, v92 dst_sel:DWORD dst_unused:UNUSED_PAD src0_sel:WORD_1
	v_cvt_f32_f16_e32 v120, v93
	v_cvt_f32_f16_sdwa v121, v93 dst_sel:DWORD dst_unused:UNUSED_PAD src0_sel:WORD_1
	v_cvt_f32_f16_e32 v122, v94
	v_cvt_f32_f16_sdwa v123, v94 dst_sel:DWORD dst_unused:UNUSED_PAD src0_sel:WORD_1
	v_cvt_f32_f16_e32 v124, v95
	v_cvt_f32_f16_sdwa v125, v95 dst_sel:DWORD dst_unused:UNUSED_PAD src0_sel:WORD_1
	v_pk_add_f32 v[58:59], v[58:59], v[74:75]
	v_pk_add_f32 v[74:75], v[54:55], v[76:77]
	v_pk_add_f32 v[78:79], v[50:51], v[78:79]
	v_pk_add_f32 v[76:77], v[48:49], v[102:103]
	v_pk_add_f32 v[94:95], v[42:43], v[108:109]
	v_pk_add_f32 v[92:93], v[40:41], v[106:107]
	v_pk_add_f32 v[50:51], v[38:39], v[84:85]
	v_pk_add_f32 v[48:49], v[36:37], v[110:111]
	v_pk_add_f32 v[42:43], v[34:35], v[86:87]
	v_pk_add_f32 v[40:41], v[32:33], v[112:113]
	v_pk_add_f32 v[38:39], v[30:31], v[88:89]
	v_pk_add_f32 v[36:37], v[28:29], v[114:115]
	v_pk_add_f32 v[34:35], v[26:27], v[90:91]
	v_pk_add_f32 v[32:33], v[24:25], v[116:117]
	s_waitcnt vmcnt(1)
	v_cvt_f32_f16_e32 v24, v68
	v_cvt_f32_f16_sdwa v25, v68 dst_sel:DWORD dst_unused:UNUSED_PAD src0_sel:WORD_1
	v_cvt_f32_f16_e32 v26, v69
	v_cvt_f32_f16_sdwa v27, v69 dst_sel:DWORD dst_unused:UNUSED_PAD src0_sel:WORD_1
	v_cvt_f32_f16_e32 v28, v70
	v_cvt_f32_f16_e32 v30, v71
	v_cvt_f32_f16_sdwa v31, v71 dst_sel:DWORD dst_unused:UNUSED_PAD src0_sel:WORD_1
	v_cvt_f32_f16_sdwa v29, v70 dst_sel:DWORD dst_unused:UNUSED_PAD src0_sel:WORD_1
	v_pk_add_f32 v[62:63], v[62:63], v[72:73]
	v_pk_add_f32 v[60:61], v[60:61], v[96:97]
	v_pk_add_f32 v[56:57], v[56:57], v[98:99]
	v_pk_add_f32 v[72:73], v[52:53], v[100:101]
	v_pk_add_f32 v[82:83], v[46:47], v[80:81]
	v_pk_add_f32 v[80:81], v[44:45], v[104:105]
	v_pk_add_f32 v[14:15], v[14:15], v[26:27]
	v_pk_add_f32 v[12:13], v[12:13], v[24:25]
	v_pk_add_f32 v[10:11], v[10:11], v[30:31]
	v_pk_add_f32 v[8:9], v[8:9], v[28:29]
	s_waitcnt vmcnt(0)
	v_cvt_f32_f16_e32 v24, v64
	v_cvt_f32_f16_sdwa v25, v64 dst_sel:DWORD dst_unused:UNUSED_PAD src0_sel:WORD_1
	v_cvt_f32_f16_e32 v26, v65
	v_cvt_f32_f16_sdwa v27, v65 dst_sel:DWORD dst_unused:UNUSED_PAD src0_sel:WORD_1
	v_cvt_f32_f16_e32 v28, v66
	v_cvt_f32_f16_e32 v30, v67
	v_cvt_f32_f16_sdwa v31, v67 dst_sel:DWORD dst_unused:UNUSED_PAD src0_sel:WORD_1
	v_cvt_f32_f16_sdwa v29, v66 dst_sel:DWORD dst_unused:UNUSED_PAD src0_sel:WORD_1
	v_pk_add_f32 v[22:23], v[22:23], v[120:121]
	v_pk_add_f32 v[20:21], v[20:21], v[118:119]
	v_pk_add_f32 v[18:19], v[18:19], v[124:125]
	v_pk_add_f32 v[16:17], v[16:17], v[122:123]
	v_pk_add_f32 v[6:7], v[6:7], v[26:27]
	v_pk_add_f32 v[4:5], v[4:5], v[24:25]
	v_pk_add_f32 v[2:3], v[2:3], v[30:31]
	v_pk_add_f32 v[0:1], v[0:1], v[28:29]
	s_nop 0
	buffer_load_dwordx4 v[24:27], v189, s[4:7], s40 offen
	s_add_i32 s40, s35, 0x38400
	buffer_load_dwordx4 v[28:31], v189, s[4:7], s40 offen
	s_add_i32 s40, s35, 0x38800
	buffer_load_dwordx4 v[64:67], v189, s[4:7], s40 offen
	s_add_i32 s40, s35, 0x38c00
	buffer_load_dwordx4 v[68:71], v189, s[4:7], s40 offen
	s_add_i32 s40, s35, 0x39000
	buffer_load_dwordx4 v[96:99], v189, s[4:7], s40 offen
	s_add_i32 s40, s35, 0x39400
	buffer_load_dwordx4 v[100:103], v189, s[4:7], s40 offen
	s_add_i32 s40, s35, 0x39800
	s_add_i32 s35, s35, 0x39c00
	buffer_load_dwordx4 v[52:55], v189, s[4:7], s40 offen
	buffer_load_dwordx4 v[44:47], v189, s[4:7], s35 offen
	s_and_b32 s35, s63, 3
	s_or_b32 s35, s35, s37
	s_mul_i32 s35, s35, 0x18000
	s_add_i32 s31, s31, s35
	s_or_b32 s35, s31, 0x400
	s_waitcnt vmcnt(7)
	v_cvt_f32_f16_e32 v84, v24
	v_cvt_f32_f16_sdwa v85, v24 dst_sel:DWORD dst_unused:UNUSED_PAD src0_sel:WORD_1
	v_cvt_f32_f16_e32 v86, v26
	v_cvt_f32_f16_sdwa v87, v26 dst_sel:DWORD dst_unused:UNUSED_PAD src0_sel:WORD_1
	s_waitcnt vmcnt(6)
	v_cvt_f32_f16_e32 v88, v28
	v_cvt_f32_f16_sdwa v89, v28 dst_sel:DWORD dst_unused:UNUSED_PAD src0_sel:WORD_1
	v_cvt_f32_f16_e32 v28, v29
	v_cvt_f32_f16_sdwa v29, v29 dst_sel:DWORD dst_unused:UNUSED_PAD src0_sel:WORD_1
	v_cvt_f32_f16_e32 v108, v30
	v_cvt_f32_f16_sdwa v109, v30 dst_sel:DWORD dst_unused:UNUSED_PAD src0_sel:WORD_1
	v_cvt_f32_f16_e32 v30, v31
	v_cvt_f32_f16_sdwa v31, v31 dst_sel:DWORD dst_unused:UNUSED_PAD src0_sel:WORD_1
	v_cvt_f32_f16_e32 v24, v25
	v_cvt_f32_f16_sdwa v25, v25 dst_sel:DWORD dst_unused:UNUSED_PAD src0_sel:WORD_1
	v_cvt_f32_f16_e32 v26, v27
	v_cvt_f32_f16_sdwa v27, v27 dst_sel:DWORD dst_unused:UNUSED_PAD src0_sel:WORD_1
	s_waitcnt vmcnt(4)
	v_cvt_f32_f16_e32 v116, v68
	v_cvt_f32_f16_sdwa v117, v68 dst_sel:DWORD dst_unused:UNUSED_PAD src0_sel:WORD_1
	v_cvt_f32_f16_e32 v68, v69
	v_cvt_f32_f16_sdwa v69, v69 dst_sel:DWORD dst_unused:UNUSED_PAD src0_sel:WORD_1
	v_pk_add_f32 v[104:105], v[60:61], v[84:85]
	v_pk_add_f32 v[60:61], v[56:57], v[86:87]
	v_pk_add_f32 v[90:91], v[74:75], v[28:29]
	v_pk_add_f32 v[86:87], v[78:79], v[30:31]
	v_cvt_f32_f16_e32 v28, v70
	v_cvt_f32_f16_e32 v30, v71
	v_cvt_f32_f16_sdwa v31, v71 dst_sel:DWORD dst_unused:UNUSED_PAD src0_sel:WORD_1
	v_cvt_f32_f16_sdwa v29, v70 dst_sel:DWORD dst_unused:UNUSED_PAD src0_sel:WORD_1
	v_pk_add_f32 v[106:107], v[62:63], v[24:25]
	v_pk_add_f32 v[62:63], v[58:59], v[26:27]
	v_pk_add_f32 v[26:27], v[50:51], v[68:69]
	v_pk_add_f32 v[24:25], v[48:49], v[116:117]
	v_pk_add_f32 v[30:31], v[42:43], v[30:31]
	v_pk_add_f32 v[28:29], v[40:41], v[28:29]
	s_waitcnt vmcnt(3)
	v_cvt_f32_f16_e32 v40, v96
	v_cvt_f32_f16_sdwa v41, v96 dst_sel:DWORD dst_unused:UNUSED_PAD src0_sel:WORD_1
	v_cvt_f32_f16_e32 v42, v97
	v_cvt_f32_f16_sdwa v43, v97 dst_sel:DWORD dst_unused:UNUSED_PAD src0_sel:WORD_1
	v_cvt_f32_f16_e32 v48, v98
	v_cvt_f32_f16_e32 v50, v99
	v_cvt_f32_f16_sdwa v51, v99 dst_sel:DWORD dst_unused:UNUSED_PAD src0_sel:WORD_1
	v_cvt_f32_f16_sdwa v49, v98 dst_sel:DWORD dst_unused:UNUSED_PAD src0_sel:WORD_1
	v_pk_add_f32 v[38:39], v[38:39], v[42:43]
	v_pk_add_f32 v[36:37], v[36:37], v[40:41]
	v_pk_add_f32 v[42:43], v[34:35], v[50:51]
	v_pk_add_f32 v[40:41], v[32:33], v[48:49]
	s_waitcnt vmcnt(2)
	v_cvt_f32_f16_e32 v32, v100
	v_cvt_f32_f16_sdwa v33, v100 dst_sel:DWORD dst_unused:UNUSED_PAD src0_sel:WORD_1
	v_cvt_f32_f16_e32 v34, v101
	v_cvt_f32_f16_sdwa v35, v101 dst_sel:DWORD dst_unused:UNUSED_PAD src0_sel:WORD_1
	v_cvt_f32_f16_e32 v110, v64
	v_cvt_f32_f16_sdwa v111, v64 dst_sel:DWORD dst_unused:UNUSED_PAD src0_sel:WORD_1
	v_cvt_f32_f16_e32 v64, v65
	v_cvt_f32_f16_sdwa v65, v65 dst_sel:DWORD dst_unused:UNUSED_PAD src0_sel:WORD_1
	v_cvt_f32_f16_e32 v112, v66
	v_cvt_f32_f16_sdwa v113, v66 dst_sel:DWORD dst_unused:UNUSED_PAD src0_sel:WORD_1
	v_cvt_f32_f16_e32 v114, v67
	v_cvt_f32_f16_sdwa v115, v67 dst_sel:DWORD dst_unused:UNUSED_PAD src0_sel:WORD_1
	v_cvt_f32_f16_e32 v48, v102
	v_cvt_f32_f16_e32 v50, v103
	v_cvt_f32_f16_sdwa v51, v103 dst_sel:DWORD dst_unused:UNUSED_PAD src0_sel:WORD_1
	v_cvt_f32_f16_sdwa v49, v102 dst_sel:DWORD dst_unused:UNUSED_PAD src0_sel:WORD_1
	v_pk_add_f32 v[22:23], v[22:23], v[34:35]
	v_pk_add_f32 v[20:21], v[20:21], v[32:33]
	s_waitcnt vmcnt(1)
	v_cvt_f32_f16_e32 v32, v52
	v_cvt_f32_f16_sdwa v33, v52 dst_sel:DWORD dst_unused:UNUSED_PAD src0_sel:WORD_1
	v_cvt_f32_f16_e32 v34, v53
	v_cvt_f32_f16_sdwa v35, v53 dst_sel:DWORD dst_unused:UNUSED_PAD src0_sel:WORD_1
	v_cvt_f32_f16_e32 v52, v54
	v_cvt_f32_f16_e32 v68, v55
	v_cvt_f32_f16_sdwa v69, v55 dst_sel:DWORD dst_unused:UNUSED_PAD src0_sel:WORD_1
	v_cvt_f32_f16_sdwa v53, v54 dst_sel:DWORD dst_unused:UNUSED_PAD src0_sel:WORD_1
	v_pk_add_f32 v[88:89], v[72:73], v[88:89]
	v_pk_add_f32 v[84:85], v[76:77], v[108:109]
	v_pk_add_f32 v[66:67], v[82:83], v[64:65]
	v_pk_add_f32 v[64:65], v[80:81], v[110:111]
	v_pk_add_f32 v[58:59], v[94:95], v[114:115]
	v_pk_add_f32 v[56:57], v[92:93], v[112:113]
	v_pk_add_f32 v[18:19], v[18:19], v[50:51]
	v_pk_add_f32 v[16:17], v[16:17], v[48:49]
	v_pk_add_f32 v[50:51], v[14:15], v[34:35]
	v_pk_add_f32 v[48:49], v[12:13], v[32:33]
	v_pk_add_f32 v[54:55], v[10:11], v[68:69]
	v_pk_add_f32 v[52:53], v[8:9], v[52:53]
	s_waitcnt vmcnt(0)
	v_cvt_f32_f16_e32 v8, v44
	v_cvt_f32_f16_sdwa v9, v44 dst_sel:DWORD dst_unused:UNUSED_PAD src0_sel:WORD_1
	v_cvt_f32_f16_e32 v10, v45
	v_cvt_f32_f16_sdwa v11, v45 dst_sel:DWORD dst_unused:UNUSED_PAD src0_sel:WORD_1
	v_cvt_f32_f16_e32 v12, v46
	v_cvt_f32_f16_e32 v14, v47
	v_cvt_f32_f16_sdwa v15, v47 dst_sel:DWORD dst_unused:UNUSED_PAD src0_sel:WORD_1
	v_cvt_f32_f16_sdwa v13, v46 dst_sel:DWORD dst_unused:UNUSED_PAD src0_sel:WORD_1
	v_pk_add_f32 v[74:75], v[6:7], v[10:11]
	v_pk_add_f32 v[72:73], v[4:5], v[8:9]
	v_pk_add_f32 v[78:79], v[2:3], v[14:15]
	v_pk_add_f32 v[76:77], v[0:1], v[12:13]
	s_nop 0
	buffer_load_dwordx4 v[0:3], v189, s[4:7], s31 offen
	buffer_load_dwordx4 v[4:7], v189, s[4:7], s35 offen
	s_or_b32 s35, s31, 0x800
	buffer_load_dwordx4 v[8:11], v189, s[4:7], s35 offen
	s_or_b32 s35, s31, 0xc00
	buffer_load_dwordx4 v[96:99], v189, s[4:7], s35 offen
	s_or_b32 s35, s31, 0x1000
	buffer_load_dwordx4 v[100:103], v189, s[4:7], s35 offen
	s_or_b32 s35, s31, 0x1400
	buffer_load_dwordx4 v[108:111], v189, s[4:7], s35 offen
	s_or_b32 s35, s31, 0x1800
	s_or_b32 s31, s31, 0x1c00
	buffer_load_dwordx4 v[92:95], v189, s[4:7], s35 offen
	buffer_load_dwordx4 v[80:83], v189, s[4:7], s31 offen
	v_ashrrev_i32_e32 v189, 31, v188
	s_waitcnt vmcnt(7)
	v_cvt_f32_f16_e32 v12, v0
	v_cvt_f32_f16_sdwa v13, v0 dst_sel:DWORD dst_unused:UNUSED_PAD src0_sel:WORD_1
	v_cvt_f32_f16_e32 v0, v1
	v_cvt_f32_f16_sdwa v1, v1 dst_sel:DWORD dst_unused:UNUSED_PAD src0_sel:WORD_1
	v_cvt_f32_f16_e32 v14, v2
	v_cvt_f32_f16_e32 v32, v3
	v_cvt_f32_f16_sdwa v33, v3 dst_sel:DWORD dst_unused:UNUSED_PAD src0_sel:WORD_1
	v_cvt_f32_f16_sdwa v15, v2 dst_sel:DWORD dst_unused:UNUSED_PAD src0_sel:WORD_1
	v_pk_add_f32 v[70:71], v[106:107], v[0:1]
	s_waitcnt vmcnt(6)
	v_cvt_f32_f16_e32 v0, v4
	v_cvt_f32_f16_sdwa v1, v4 dst_sel:DWORD dst_unused:UNUSED_PAD src0_sel:WORD_1
	v_cvt_f32_f16_e32 v2, v5
	v_cvt_f32_f16_sdwa v3, v5 dst_sel:DWORD dst_unused:UNUSED_PAD src0_sel:WORD_1
	v_cvt_f32_f16_e32 v4, v6
	v_cvt_f32_f16_sdwa v5, v6 dst_sel:DWORD dst_unused:UNUSED_PAD src0_sel:WORD_1
	v_pk_add_f32 v[68:69], v[104:105], v[12:13]
	v_pk_add_f32 v[62:63], v[62:63], v[32:33]
	v_cvt_f32_f16_e32 v12, v7
	v_cvt_f32_f16_sdwa v13, v7 dst_sel:DWORD dst_unused:UNUSED_PAD src0_sel:WORD_1
	v_pk_add_f32 v[44:45], v[88:89], v[0:1]
	v_pk_add_f32 v[32:33], v[84:85], v[4:5]
	s_waitcnt vmcnt(5)
	v_cvt_f32_f16_e32 v0, v8
	v_cvt_f32_f16_sdwa v1, v8 dst_sel:DWORD dst_unused:UNUSED_PAD src0_sel:WORD_1
	v_cvt_f32_f16_e32 v4, v10
	v_cvt_f32_f16_sdwa v5, v10 dst_sel:DWORD dst_unused:UNUSED_PAD src0_sel:WORD_1
	v_pk_add_f32 v[46:47], v[90:91], v[2:3]
	v_pk_add_f32 v[34:35], v[86:87], v[12:13]
	v_cvt_f32_f16_e32 v2, v9
	v_cvt_f32_f16_sdwa v3, v9 dst_sel:DWORD dst_unused:UNUSED_PAD src0_sel:WORD_1
	v_cvt_f32_f16_e32 v6, v11
	v_cvt_f32_f16_sdwa v7, v11 dst_sel:DWORD dst_unused:UNUSED_PAD src0_sel:WORD_1
	v_pk_add_f32 v[12:13], v[64:65], v[0:1]
	v_pk_add_f32 v[8:9], v[56:57], v[4:5]
	s_waitcnt vmcnt(4)
	v_cvt_f32_f16_e32 v0, v96
	v_cvt_f32_f16_sdwa v1, v96 dst_sel:DWORD dst_unused:UNUSED_PAD src0_sel:WORD_1
	v_cvt_f32_f16_e32 v56, v98
	v_cvt_f32_f16_sdwa v57, v98 dst_sel:DWORD dst_unused:UNUSED_PAD src0_sel:WORD_1
	v_pk_add_f32 v[60:61], v[60:61], v[14:15]
	v_pk_add_f32 v[14:15], v[66:67], v[2:3]
	v_pk_add_f32 v[10:11], v[58:59], v[6:7]
	v_cvt_f32_f16_e32 v2, v97
	v_cvt_f32_f16_sdwa v3, v97 dst_sel:DWORD dst_unused:UNUSED_PAD src0_sel:WORD_1
	v_cvt_f32_f16_e32 v58, v99
	v_cvt_f32_f16_sdwa v59, v99 dst_sel:DWORD dst_unused:UNUSED_PAD src0_sel:WORD_1
	v_pk_add_f32 v[4:5], v[24:25], v[0:1]
	v_pk_add_f32 v[0:1], v[28:29], v[56:57]
	s_waitcnt vmcnt(3)
	v_cvt_f32_f16_e32 v28, v102
	v_cvt_f32_f16_sdwa v29, v102 dst_sel:DWORD dst_unused:UNUSED_PAD src0_sel:WORD_1
	v_pk_add_f32 v[6:7], v[26:27], v[2:3]
	v_pk_add_f32 v[2:3], v[30:31], v[58:59]
	v_cvt_f32_f16_e32 v24, v100
	v_cvt_f32_f16_sdwa v25, v100 dst_sel:DWORD dst_unused:UNUSED_PAD src0_sel:WORD_1
	v_cvt_f32_f16_e32 v30, v103
	v_cvt_f32_f16_sdwa v31, v103 dst_sel:DWORD dst_unused:UNUSED_PAD src0_sel:WORD_1
	v_pk_add_f32 v[88:89], v[40:41], v[28:29]
	s_waitcnt vmcnt(2)
	v_cvt_f32_f16_e32 v28, v110
	v_cvt_f32_f16_sdwa v29, v110 dst_sel:DWORD dst_unused:UNUSED_PAD src0_sel:WORD_1
	v_cvt_f32_f16_e32 v26, v101
	v_cvt_f32_f16_sdwa v27, v101 dst_sel:DWORD dst_unused:UNUSED_PAD src0_sel:WORD_1
	v_pk_add_f32 v[84:85], v[36:37], v[24:25]
	v_pk_add_f32 v[90:91], v[42:43], v[30:31]
	v_cvt_f32_f16_e32 v24, v108
	v_cvt_f32_f16_sdwa v25, v108 dst_sel:DWORD dst_unused:UNUSED_PAD src0_sel:WORD_1
	v_cvt_f32_f16_e32 v30, v111
	v_cvt_f32_f16_sdwa v31, v111 dst_sel:DWORD dst_unused:UNUSED_PAD src0_sel:WORD_1
	v_pk_add_f32 v[64:65], v[16:17], v[28:29]
	s_waitcnt vmcnt(1)
	v_cvt_f32_f16_e32 v16, v92
	v_cvt_f32_f16_sdwa v17, v92 dst_sel:DWORD dst_unused:UNUSED_PAD src0_sel:WORD_1
	v_pk_add_f32 v[86:87], v[38:39], v[26:27]
	v_cvt_f32_f16_e32 v26, v109
	v_cvt_f32_f16_sdwa v27, v109 dst_sel:DWORD dst_unused:UNUSED_PAD src0_sel:WORD_1
	v_pk_add_f32 v[56:57], v[20:21], v[24:25]
	v_pk_add_f32 v[66:67], v[18:19], v[30:31]
	v_cvt_f32_f16_e32 v18, v93
	v_cvt_f32_f16_sdwa v19, v93 dst_sel:DWORD dst_unused:UNUSED_PAD src0_sel:WORD_1
	v_cvt_f32_f16_e32 v20, v94
	v_cvt_f32_f16_sdwa v21, v94 dst_sel:DWORD dst_unused:UNUSED_PAD src0_sel:WORD_1
	v_pk_add_f32 v[36:37], v[48:49], v[16:17]
	s_waitcnt vmcnt(0)
	v_cvt_f32_f16_e32 v16, v80
	v_cvt_f32_f16_sdwa v17, v80 dst_sel:DWORD dst_unused:UNUSED_PAD src0_sel:WORD_1
	v_cvt_f32_f16_e32 v24, v82
	v_cvt_f32_f16_sdwa v25, v82 dst_sel:DWORD dst_unused:UNUSED_PAD src0_sel:WORD_1
	v_pk_add_f32 v[58:59], v[22:23], v[26:27]
	v_cvt_f32_f16_e32 v22, v95
	v_cvt_f32_f16_sdwa v23, v95 dst_sel:DWORD dst_unused:UNUSED_PAD src0_sel:WORD_1
	v_pk_add_f32 v[38:39], v[50:51], v[18:19]
	v_pk_add_f32 v[40:41], v[52:53], v[20:21]
	v_cvt_f32_f16_e32 v18, v81
	v_cvt_f32_f16_sdwa v19, v81 dst_sel:DWORD dst_unused:UNUSED_PAD src0_sel:WORD_1
	v_cvt_f32_f16_e32 v26, v83
	v_cvt_f32_f16_sdwa v27, v83 dst_sel:DWORD dst_unused:UNUSED_PAD src0_sel:WORD_1
	v_pk_add_f32 v[20:21], v[72:73], v[16:17]
	v_pk_add_f32 v[16:17], v[76:77], v[24:25]
	v_and_b32_e32 v24, 1, v197
	v_add_u32_e32 v25, 12, v199
	v_cmp_eq_u32_e32 vcc, 0, v24
	v_pk_add_f32 v[42:43], v[54:55], v[22:23]
	v_pk_add_f32 v[22:23], v[74:75], v[18:19]
	v_cndmask_b32_e32 v24, v25, v199, vcc
	v_add_u32_e32 v24, v24, v198
	v_pk_add_f32 v[18:19], v[78:79], v[26:27]
	v_ashrrev_i32_e32 v25, 31, v24
	v_lshlrev_b64 v[26:27], 11, v[188:189]
	v_lshl_add_u64 v[26:27], v[170:171], 0, v[26:27]
	v_lshlrev_b64 v[72:73], 1, v[24:25]
	v_lshl_add_u64 v[78:79], v[26:27], 0, v[72:73]
	global_load_dwordx4 v[52:55], v[190:191], off
	global_load_dwordx4 v[48:51], v[190:191], off offset:64
	global_load_dwordx4 v[28:31], v[190:191], off offset:512
	global_load_dwordx4 v[24:27], v[190:191], off offset:576
	s_mov_b64 s[78:79], 0x8000
	v_mov_b32_e32 v250, v78
	v_mov_b32_e32 v251, v79
	global_load_dwordx4 v[200:203], v[250:251], off
	global_load_dwordx4 v[204:207], v[250:251], off offset:256
	v_lshl_add_u64 v[250:251], v[250:251], 0, s[78:79]
	global_load_dwordx4 v[208:211], v[250:251], off
	global_load_dwordx4 v[212:215], v[250:251], off offset:256
	v_lshl_add_u64 v[250:251], v[250:251], 0, s[78:79]
	global_load_dwordx4 v[216:219], v[250:251], off
	s_waitcnt vmcnt(4)
	s_nop 1
	v_mov_b32_e32 v74, v200
	v_mov_b32_e32 v75, v201
	v_mov_b32_e32 v76, v202
	v_mov_b32_e32 v77, v203
	global_load_dwordx4 v[200:203], v[250:251], off offset:256
	s_nop 1
	v_permlane16_swap_b32_e32 v74, v76
	v_permlane16_swap_b32_e32 v75, v77
	v_lshlrev_b32_e32 v80, 16, v74
	v_and_b32_e32 v81, 0xffff0000, v74
	v_lshlrev_b32_e32 v74, 16, v75
	v_and_b32_e32 v75, 0xffff0000, v75
	v_lshlrev_b32_e32 v82, 16, v76
	v_and_b32_e32 v83, 0xffff0000, v76
	v_lshlrev_b32_e32 v92, 16, v77
	v_and_b32_e32 v93, 0xffff0000, v77
	v_pk_fma_f32 v[76:77], v[70:71], v[54:55], v[74:75]
	v_pk_fma_f32 v[74:75], v[68:69], v[52:53], v[80:81]
	v_lshlrev_b64 v[68:69], 12, v[188:189]
	v_lshl_add_u64 v[70:71], s[0:1], 0, v[68:69]
	v_lshlrev_b64 v[68:69], 2, v[186:187]
	v_lshl_add_u64 v[70:71], v[70:71], 0, v[68:69]
	v_pk_fma_f32 v[62:63], v[62:63], v[50:51], v[92:93]
	v_pk_fma_f32 v[60:61], v[60:61], v[48:49], v[82:83]
	global_store_dwordx4 v[70:71], v[74:77], off
	global_store_dwordx4 v[70:71], v[60:63], off offset:64
	v_add_u32_e32 v78, 16, v188
	v_ashrrev_i32_e32 v79, 31, v78
	v_lshlrev_b64 v[74:75], 11, v[78:79]
	v_lshl_add_u64 v[74:75], v[170:171], 0, v[74:75]
	v_lshl_add_u64 v[80:81], v[74:75], 0, v[72:73]
	s_waitcnt vmcnt(6)
	s_nop 1
	v_mov_b32_e32 v60, v204
	v_mov_b32_e32 v61, v205
	v_mov_b32_e32 v62, v206
	v_mov_b32_e32 v63, v207
	v_lshl_add_u64 v[250:251], v[250:251], 0, s[78:79]
	global_load_dwordx4 v[204:207], v[250:251], off
	s_nop 1
	v_permlane16_swap_b32_e32 v60, v62
	v_permlane16_swap_b32_e32 v61, v63
	v_lshlrev_b32_e32 v74, 16, v60
	v_and_b32_e32 v75, 0xffff0000, v60
	v_lshlrev_b32_e32 v60, 16, v61
	v_and_b32_e32 v61, 0xffff0000, v61
	v_lshlrev_b32_e32 v82, 16, v62
	v_and_b32_e32 v83, 0xffff0000, v62
	v_lshlrev_b32_e32 v76, 16, v63
	v_and_b32_e32 v77, 0xffff0000, v63
	v_pk_fma_f32 v[62:63], v[86:87], v[30:31], v[60:61]
	v_pk_fma_f32 v[60:61], v[84:85], v[28:29], v[74:75]
	v_pk_fma_f32 v[76:77], v[90:91], v[26:27], v[76:77]
	v_pk_fma_f32 v[74:75], v[88:89], v[24:25], v[82:83]
	global_store_dwordx4 v[70:71], v[60:63], off offset:512
	global_store_dwordx4 v[70:71], v[74:77], off offset:576
	v_lshlrev_b64 v[70:71], 12, v[78:79]
	v_lshl_add_u64 v[70:71], s[0:1], 0, v[70:71]
	v_lshl_add_u64 v[70:71], v[70:71], 0, v[68:69]
	s_waitcnt vmcnt(8)
	s_nop 1
	v_mov_b32_e32 v60, v208
	v_mov_b32_e32 v61, v209
	v_mov_b32_e32 v62, v210
	v_mov_b32_e32 v63, v211
	global_load_dwordx4 v[208:211], v[250:251], off offset:256
	s_nop 1
	v_mov_b32_e32 v75, v62
	v_mov_b32_e32 v77, v63
	s_nop 0
	v_permlane16_swap_b32_e32 v60, v75
	v_permlane16_swap_b32_e32 v61, v77
	v_lshlrev_b32_e32 v62, 16, v60
	v_and_b32_e32 v63, 0xffff0000, v60
	v_lshlrev_b32_e32 v60, 16, v61
	v_and_b32_e32 v61, 0xffff0000, v61
	v_lshlrev_b32_e32 v74, 16, v75
	v_and_b32_e32 v75, 0xffff0000, v75
	v_lshlrev_b32_e32 v76, 16, v77
	v_and_b32_e32 v77, 0xffff0000, v77
	v_pk_fma_f32 v[46:47], v[46:47], v[54:55], v[60:61]
	v_pk_fma_f32 v[44:45], v[44:45], v[52:53], v[62:63]
	v_pk_fma_f32 v[34:35], v[34:35], v[50:51], v[76:77]
	v_pk_fma_f32 v[32:33], v[32:33], v[48:49], v[74:75]
	global_store_dwordx4 v[70:71], v[44:47], off
	global_store_dwordx4 v[70:71], v[32:35], off offset:64
	v_add_u32_e32 v60, 32, v188
	v_ashrrev_i32_e32 v61, 31, v60
	v_lshlrev_b64 v[44:45], 11, v[60:61]
	v_lshl_add_u64 v[44:45], v[170:171], 0, v[44:45]
	v_lshl_add_u64 v[62:63], v[44:45], 0, v[72:73]
	s_waitcnt vmcnt(10)
	s_nop 1
	v_mov_b32_e32 v32, v212
	v_mov_b32_e32 v33, v213
	v_mov_b32_e32 v34, v214
	v_mov_b32_e32 v35, v215
	s_nop 1
	v_permlane16_swap_b32_e32 v32, v34
	v_permlane16_swap_b32_e32 v33, v35
	v_lshlrev_b32_e32 v44, 16, v32
	v_and_b32_e32 v45, 0xffff0000, v32
	v_lshlrev_b32_e32 v32, 16, v33
	v_and_b32_e32 v33, 0xffff0000, v33
	v_lshlrev_b32_e32 v74, 16, v34
	v_and_b32_e32 v75, 0xffff0000, v34
	v_lshlrev_b32_e32 v46, 16, v35
	v_and_b32_e32 v47, 0xffff0000, v35
	v_pk_fma_f32 v[34:35], v[58:59], v[30:31], v[32:33]
	v_pk_fma_f32 v[32:33], v[56:57], v[28:29], v[44:45]
	v_pk_fma_f32 v[46:47], v[66:67], v[26:27], v[46:47]
	v_pk_fma_f32 v[44:45], v[64:65], v[24:25], v[74:75]
	global_store_dwordx4 v[70:71], v[32:35], off offset:512
	global_store_dwordx4 v[70:71], v[44:47], off offset:576
	s_waitcnt vmcnt(11)
	s_nop 1
	v_mov_b32_e32 v32, v216
	v_mov_b32_e32 v33, v217
	v_mov_b32_e32 v34, v218
	v_mov_b32_e32 v35, v219
	s_nop 1
	v_mov_b32_e32 v57, v35
	v_mov_b32_e32 v47, v34
	v_lshlrev_b64 v[44:45], 12, v[60:61]
	s_nop 0
	v_permlane16_swap_b32_e32 v32, v47
	v_permlane16_swap_b32_e32 v33, v57
	v_lshl_add_u64 v[44:45], s[0:1], 0, v[44:45]
	v_lshlrev_b32_e32 v34, 16, v32
	v_and_b32_e32 v35, 0xffff0000, v32
	v_lshlrev_b32_e32 v32, 16, v33
	v_and_b32_e32 v33, 0xffff0000, v33
	v_lshl_add_u64 v[44:45], v[44:45], 0, v[68:69]
	v_lshlrev_b32_e32 v46, 16, v47
	v_and_b32_e32 v47, 0xffff0000, v47
	v_lshlrev_b32_e32 v56, 16, v57
	v_and_b32_e32 v57, 0xffff0000, v57
	v_pk_fma_f32 v[14:15], v[14:15], v[54:55], v[32:33]
	v_pk_fma_f32 v[12:13], v[12:13], v[52:53], v[34:35]
	v_pk_fma_f32 v[10:11], v[10:11], v[50:51], v[56:57]
	v_pk_fma_f32 v[8:9], v[8:9], v[48:49], v[46:47]
	global_store_dwordx4 v[44:45], v[12:15], off
	global_store_dwordx4 v[44:45], v[8:11], off offset:64
	v_add_u32_e32 v32, 48, v188
	v_ashrrev_i32_e32 v33, 31, v32
	v_lshlrev_b64 v[12:13], 11, v[32:33]
	v_lshl_add_u64 v[12:13], v[170:171], 0, v[12:13]
	v_lshl_add_u64 v[34:35], v[12:13], 0, v[72:73]
	v_lshlrev_b64 v[136:137], 10, v[32:33]
	s_waitcnt vmcnt(12)
	s_nop 1
	v_mov_b32_e32 v8, v200
	v_mov_b32_e32 v9, v201
	v_mov_b32_e32 v10, v202
	v_mov_b32_e32 v11, v203
	s_nop 1
	v_permlane16_swap_b32_e32 v8, v10
	v_permlane16_swap_b32_e32 v9, v11
	v_lshlrev_b32_e32 v12, 16, v8
	v_and_b32_e32 v13, 0xffff0000, v8
	v_lshlrev_b32_e32 v8, 16, v9
	v_and_b32_e32 v9, 0xffff0000, v9
	v_lshlrev_b32_e32 v46, 16, v10
	v_and_b32_e32 v47, 0xffff0000, v10
	v_lshlrev_b32_e32 v14, 16, v11
	v_and_b32_e32 v15, 0xffff0000, v11
	v_pk_fma_f32 v[10:11], v[38:39], v[30:31], v[8:9]
	v_pk_fma_f32 v[8:9], v[36:37], v[28:29], v[12:13]
	v_pk_fma_f32 v[14:15], v[42:43], v[26:27], v[14:15]
	v_pk_fma_f32 v[12:13], v[40:41], v[24:25], v[46:47]
	global_store_dwordx4 v[44:45], v[8:11], off offset:512
	global_store_dwordx4 v[44:45], v[12:15], off offset:576
	s_waitcnt vmcnt(11)
	s_nop 1
	v_mov_b32_e32 v8, v204
	v_mov_b32_e32 v9, v205
	v_mov_b32_e32 v10, v206
	v_mov_b32_e32 v11, v207
	s_nop 1
	v_mov_b32_e32 v37, v11
	v_mov_b32_e32 v15, v10
	v_lshlrev_b64 v[12:13], 12, v[32:33]
	s_nop 0
	v_permlane16_swap_b32_e32 v8, v15
	v_permlane16_swap_b32_e32 v9, v37
	v_lshl_add_u64 v[12:13], s[0:1], 0, v[12:13]
	v_lshlrev_b32_e32 v10, 16, v8
	v_and_b32_e32 v11, 0xffff0000, v8
	v_lshlrev_b32_e32 v8, 16, v9
	v_and_b32_e32 v9, 0xffff0000, v9
	v_lshl_add_u64 v[12:13], v[12:13], 0, v[68:69]
	v_lshlrev_b32_e32 v14, 16, v15
	v_and_b32_e32 v15, 0xffff0000, v15
	v_lshlrev_b32_e32 v36, 16, v37
	v_and_b32_e32 v37, 0xffff0000, v37
	v_pk_fma_f32 v[6:7], v[6:7], v[54:55], v[8:9]
	v_pk_fma_f32 v[4:5], v[4:5], v[52:53], v[10:11]
	v_pk_fma_f32 v[2:3], v[2:3], v[50:51], v[36:37]
	v_pk_fma_f32 v[0:1], v[0:1], v[48:49], v[14:15]
	global_store_dwordx4 v[12:13], v[4:7], off
	global_store_dwordx4 v[12:13], v[0:3], off offset:64
	s_waitcnt vmcnt(10)
	s_nop 1
	v_mov_b32_e32 v0, v208
	v_mov_b32_e32 v1, v209
	v_mov_b32_e32 v2, v210
	v_mov_b32_e32 v3, v211
	s_nop 1
	v_permlane16_swap_b32_e32 v0, v2
	v_permlane16_swap_b32_e32 v1, v3
	v_lshlrev_b32_e32 v4, 16, v0
	v_and_b32_e32 v5, 0xffff0000, v0
	v_lshlrev_b32_e32 v0, 16, v1
	v_and_b32_e32 v1, 0xffff0000, v1
	v_lshlrev_b32_e32 v6, 16, v2
	v_and_b32_e32 v7, 0xffff0000, v2
	v_lshlrev_b32_e32 v8, 16, v3
	v_and_b32_e32 v9, 0xffff0000, v3
	v_pk_fma_f32 v[2:3], v[22:23], v[30:31], v[0:1]
	v_pk_fma_f32 v[0:1], v[20:21], v[28:29], v[4:5]
	v_pk_fma_f32 v[130:131], v[18:19], v[26:27], v[8:9]
	v_pk_fma_f32 v[128:129], v[16:17], v[24:25], v[6:7]
	global_store_dwordx4 v[12:13], v[0:3], off offset:512
